# v18 + software-pipelined phase_final (3 rows in flight) + software-pipelined phase_hfin (6 rows of od0/od1/gate loads in flight per wave, scalar addressing)
# speedup vs baseline: 1.0063x; 1.0063x over previous
; __device__ __forceinline__ int opaque_tid() { int t = threadIdx.x; asm volatile("" : "+v"(t)); return t; }
; __device__ __forceinline__ unsigned pk2(float lo, float hi) { f32x2_t v = {lo, hi}; bf16x2_t b = __builtin_convertvector(v, bf16x2_t); return __builtin_bit_cast(unsigned, b); }
; __device__ __forceinline__ void phase_hfin(const Params& P, int l) {
;     const float* od0 = (const float*)(P.ws + WS_ODIR); const float* od1 = od0 + (size_t)ROWS * 256;
;     const bf16_t* proj = (const bf16_t*)(P.ws + WS_PROJ); bf16_t* mix = (bf16_t*)(P.ws + WS_H);
;     const float* gn = P.hgrn_norm + (size_t)l * 64;
;     const long total = (long)ROWS * 4 * 16;
;     const int tid = opaque_tid(), lane = tid & 63;
;     const long S = (long)gridDim.x * 512;
;     const int sub = tid & 15; const f32x4 gg = *(const f32x4*)(gn + sub * 4);
;     for (long i0 = (long)blockIdx.x * 512 + tid; i0 < total; i0 += 3 * S) {
;         f32x4 a[3], b2[3]; u32x2 gw[3];
; #pragma unroll
;         for (int u = 0; u < 3; ++u) {
;             const long i = i0 + u * S; const bool ok = i < total; const long rh = (ok ? i : i0) >> 4; const int h = (int)(rh & 3); const long r = rh >> 2;
;             const size_t off = (size_t)r * 256 + h * 64 + sub * 4;
;             a[u] = *(const f32x4*)(od0 + off); b2[u] = *(const f32x4*)(od1 + off);
;             gw[u] = *(const u32x2*)(proj + (size_t)r * INW + PB_G + h * 64 + sub * 4);
;         }
; #pragma unroll
;         for (int u = 0; u < 3; ++u) {
;             const long i = i0 + u * S; if (i >= total) break;
;             const long rh = i >> 4; const int h = (int)(rh & 3); const long r = rh >> 2;
;             const f32x4 o = a[u] + b2[u];
;             float ss = (o.x * o.x + o.y * o.y) + (o.z * o.z + o.w * o.w);
;             ss += shx(ss, 1, lane); ss += shx(ss, 2, lane); ss += shx(ss, 4, lane); ss += shx(ss, 8, lane);
;             const float rs = 1.0f / sqrtf(ss * (1.0f / 64.0f) + RMS_EPS);
;             const float g0 = bflo(gw[u].x), g1 = bfhi(gw[u].x), g2 = bflo(gw[u].y), g3 = bfhi(gw[u].y);
;             u32x2 w; w.x = pk2(o.x * rs * gg.x * (g0 * sigmoidf_(g0)), o.y * rs * gg.y * (g1 * sigmoidf_(g1))); w.y = pk2(o.z * rs * gg.z * (g2 * sigmoidf_(g2)), o.w * rs * gg.w * (g3 * sigmoidf_(g3)));
;             *(u32x2*)(mix + (size_t)r * DM + 256 + h * 64 + sub * 4) = w;
;         }
;     }
.LBB0_779:
	s_or_b64 exec, exec, s[0:1]
	s_mov_b64 s[24:25], s[28:29]
	v_mov_b32_e32 v6, v200
	v_readlane_b32 s0, v253, 50
	s_waitcnt lgkmcnt(0)
	s_barrier
	v_readlane_b32 s1, v253, 51
	v_ashrrev_i32_e32 v7, 31, v6
	s_nop 0
	v_lshl_add_u64 v[4:5], s[0:1], 0, v[6:7]
	s_mov_b64 s[0:1], 0x240000
	v_cmp_gt_i64_e32 vcc, s[0:1], v[4:5]
	s_and_saveexec_b64 s[0:1], vcc
	s_xor_b64 s[0:1], exec, s[0:1]
	s_cbranch_execz .LBB0_786
	s_load_dwordx2 s[10:11], s[24:25], 0xa0
	s_load_dwordx2 s[8:9], s[24:25], 0x58
	v_readlane_b32 s12, v255, 14
	v_readlane_b32 s13, v255, 15
	v_readlane_b32 s101, v253, 62
	v_readfirstlane_b32 s100, v200
	v_and_b32_e32 v64, 63, v200
	v_and_b32_e32 v66, 15, v200
	v_lshlrev_b32_e32 v66, 4, v66
	v_lshlrev_b32_e32 v65, 3, v64
	v_lshlrev_b32_e32 v76, 2, v64
	v_xor_b32_e32 v67, 4, v76
	v_xor_b32_e32 v68, 8, v76
	v_xor_b32_e32 v69, 16, v76
	v_xor_b32_e32 v70, 32, v76
	v_lshlrev_b32_e32 v64, 4, v64
	s_lshr_b32 s100, s100, 6
	s_add_u32 s101, s101, s100
	s_waitcnt lgkmcnt(0)
	s_add_u32 s8, s8, s12
	s_addc_u32 s9, s9, s13
	global_load_dwordx4 v[60:63], v66, s[8:9]
	s_add_u32 s24, s10, 0x1a200000
	s_addc_u32 s25, s11, 0
	s_add_u32 s36, s10, 0x1c600000
	s_addc_u32 s37, s11, 0
	s_add_u32 s38, s10, 0x9d00e00
	s_addc_u32 s39, s11, 0
	s_add_u32 s40, s10, 0x5500200
	s_addc_u32 s41, s11, 0
	s_lshl_b32 s12, s101, 10
	s_add_u32 s8, s24, s12
	s_addc_u32 s9, s25, 0
	global_load_dwordx4 v[0:3], v64, s[8:9]
	s_add_u32 s8, s36, s12
	s_addc_u32 s9, s37, 0
	global_load_dwordx4 v[4:7], v64, s[8:9]
	s_mul_i32 s12, s101, 0x1600
	s_add_u32 s8, s38, s12
	s_addc_u32 s9, s39, 0
	global_load_dwordx2 v[8:9], v65, s[8:9]
	s_add_u32 s100, s101, s68
	s_cmp_le_u32 s100, s71
	s_cselect_b32 s100, s100, s101
	s_lshl_b32 s12, s100, 10
	s_add_u32 s8, s24, s12
	s_addc_u32 s9, s25, 0
	global_load_dwordx4 v[10:13], v64, s[8:9]
	s_add_u32 s8, s36, s12
	s_addc_u32 s9, s37, 0
	global_load_dwordx4 v[14:17], v64, s[8:9]
	s_mul_i32 s12, s100, 0x1600
	s_add_u32 s8, s38, s12
	s_addc_u32 s9, s39, 0
	global_load_dwordx2 v[18:19], v65, s[8:9]
	s_mul_i32 s100, s68, 2
	s_add_u32 s100, s100, s101
	s_cmp_le_u32 s100, s71
	s_cselect_b32 s100, s100, s101
	s_lshl_b32 s12, s100, 10
	s_add_u32 s8, s24, s12
	s_addc_u32 s9, s25, 0
	global_load_dwordx4 v[20:23], v64, s[8:9]
	s_add_u32 s8, s36, s12
	s_addc_u32 s9, s37, 0
	global_load_dwordx4 v[24:27], v64, s[8:9]
	s_mul_i32 s12, s100, 0x1600
	s_add_u32 s8, s38, s12
	s_addc_u32 s9, s39, 0
	global_load_dwordx2 v[28:29], v65, s[8:9]
	s_mul_i32 s100, s68, 3
	s_add_u32 s100, s100, s101
	s_cmp_le_u32 s100, s71
	s_cselect_b32 s100, s100, s101
	s_lshl_b32 s12, s100, 10
	s_add_u32 s8, s24, s12
	s_addc_u32 s9, s25, 0
	global_load_dwordx4 v[30:33], v64, s[8:9]
	s_add_u32 s8, s36, s12
	s_addc_u32 s9, s37, 0
	global_load_dwordx4 v[34:37], v64, s[8:9]
	s_mul_i32 s12, s100, 0x1600
	s_add_u32 s8, s38, s12
	s_addc_u32 s9, s39, 0
	global_load_dwordx2 v[38:39], v65, s[8:9]
	s_mul_i32 s100, s68, 4
	s_add_u32 s100, s100, s101
	s_cmp_le_u32 s100, s71
	s_cselect_b32 s100, s100, s101
	s_lshl_b32 s12, s100, 10
	s_add_u32 s8, s24, s12
	s_addc_u32 s9, s25, 0
	global_load_dwordx4 v[40:43], v64, s[8:9]
	s_add_u32 s8, s36, s12
	s_addc_u32 s9, s37, 0
	global_load_dwordx4 v[44:47], v64, s[8:9]
	s_mul_i32 s12, s100, 0x1600
	s_add_u32 s8, s38, s12
	s_addc_u32 s9, s39, 0
	global_load_dwordx2 v[48:49], v65, s[8:9]
	s_mul_i32 s100, s68, 5
	s_add_u32 s100, s100, s101
	s_cmp_le_u32 s100, s71
	s_cselect_b32 s100, s100, s101
	s_lshl_b32 s12, s100, 10
	s_add_u32 s8, s24, s12
	s_addc_u32 s9, s25, 0
	global_load_dwordx4 v[50:53], v64, s[8:9]
	s_add_u32 s8, s36, s12
	s_addc_u32 s9, s37, 0
	global_load_dwordx4 v[54:57], v64, s[8:9]
	s_mul_i32 s12, s100, 0x1600
	s_add_u32 s8, s38, s12
	s_addc_u32 s9, s39, 0
	global_load_dwordx2 v[58:59], v65, s[8:9]
	s_waitcnt vmcnt(15)
	v_add_f32_e32 v72, v0, v4
	v_add_f32_e32 v73, v1, v5
	v_add_f32_e32 v74, v2, v6
	v_add_f32_e32 v75, v3, v7
	v_lshlrev_b32_e32 v84, 16, v8
	v_and_b32_e32 v85, 0xffff0000, v8
	v_lshlrev_b32_e32 v86, 16, v9
	v_and_b32_e32 v87, 0xffff0000, v9
	v_mul_f32_e32 v76, v73, v73
	v_mul_f32_e32 v77, v75, v75
	v_fmac_f32_e32 v76, v72, v72
	v_fmac_f32_e32 v77, v74, v74
	v_add_f32_e32 v78, v76, v77
	ds_bpermute_b32 v76, v67, v78
	v_mul_f32_e32 v88, 0xbfb8aa3b, v84
	v_mul_f32_e32 v89, 0xbfb8aa3b, v85
	v_mul_f32_e32 v90, 0xbfb8aa3b, v86
	v_mul_f32_e32 v91, 0xbfb8aa3b, v87
	s_waitcnt lgkmcnt(0)
	v_add_f32_e32 v78, v78, v76
	ds_bpermute_b32 v76, v68, v78
	v_exp_f32_e32 v88, v88
	v_exp_f32_e32 v89, v89
	v_exp_f32_e32 v90, v90
	v_exp_f32_e32 v91, v91
	s_waitcnt lgkmcnt(0)
	v_add_f32_e32 v78, v78, v76
	ds_bpermute_b32 v76, v69, v78
	v_add_f32_e32 v88, 1.0, v88
	v_add_f32_e32 v89, 1.0, v89
	v_add_f32_e32 v90, 1.0, v90
	v_add_f32_e32 v91, 1.0, v91
	s_waitcnt lgkmcnt(0)
	v_add_f32_e32 v78, v78, v76
	ds_bpermute_b32 v76, v70, v78
	v_rcp_f32_e32 v88, v88
	v_rcp_f32_e32 v89, v89
	v_rcp_f32_e32 v90, v90
	v_rcp_f32_e32 v91, v91
	s_waitcnt lgkmcnt(0)
; __device__ __forceinline__ unsigned pk2(float lo, float hi) { f32x2_t v = {lo, hi}; bf16x2_t b = __builtin_convertvector(v, bf16x2_t); return __builtin_bit_cast(unsigned, b); }
; __device__ __forceinline__ float shx(float v, int o, int lane) { return __builtin_bit_cast(float, __builtin_amdgcn_ds_bpermute((lane ^ o) << 2, __builtin_bit_cast(int, v))); }
; __device__ __forceinline__ float sigmoidf_(float z) { return __builtin_amdgcn_rcpf(1.0f + fast_exp2(-z * LOG2E)); }
; __device__ __forceinline__ void phase_hfin(const Params& P, int l) {
;     ...
;     for (long i0 = (long)blockIdx.x * 512 + tid; i0 < total; i0 += 3 * S) {
;         f32x4 a[3], b2[3]; u32x2 gw[3];
; #pragma unroll
;         for (int u = 0; u < 3; ++u) {
;             const long i = i0 + u * S; const bool ok = i < total; const long rh = (ok ? i : i0) >> 4; const int h = (int)(rh & 3); const long r = rh >> 2;
;             const size_t off = (size_t)r * 256 + h * 64 + sub * 4;
;             a[u] = *(const f32x4*)(od0 + off); b2[u] = *(const f32x4*)(od1 + off);
;             gw[u] = *(const u32x2*)(proj + (size_t)r * INW + PB_G + h * 64 + sub * 4);
;         }
; #pragma unroll
;         for (int u = 0; u < 3; ++u) {
;             const long i = i0 + u * S; if (i >= total) break;
;             const long rh = i >> 4; const int h = (int)(rh & 3); const long r = rh >> 2;
;             const f32x4 o = a[u] + b2[u];
;             float ss = (o.x * o.x + o.y * o.y) + (o.z * o.z + o.w * o.w);
;             ss += shx(ss, 1, lane); ss += shx(ss, 2, lane); ss += shx(ss, 4, lane); ss += shx(ss, 8, lane);
;             const float rs = 1.0f / sqrtf(ss * (1.0f / 64.0f) + RMS_EPS);
;             const float g0 = bflo(gw[u].x), g1 = bfhi(gw[u].x), g2 = bflo(gw[u].y), g3 = bfhi(gw[u].y);
;             u32x2 w; w.x = pk2(o.x * rs * gg.x * (g0 * sigmoidf_(g0)), o.y * rs * gg.y * (g1 * sigmoidf_(g1))); w.y = pk2(o.z * rs * gg.z * (g2 * sigmoidf_(g2)), o.w * rs * gg.w * (g3 * sigmoidf_(g3)));
;             *(u32x2*)(mix + (size_t)r * DM + 256 + h * 64 + sub * 4) = w;
;         }
	v_add_f32_e32 v78, v78, v76
	v_mul_f32_e32 v88, v88, v84
	v_mul_f32_e32 v89, v89, v85
	v_mul_f32_e32 v90, v90, v86
	v_mul_f32_e32 v91, v91, v87
	v_fmamk_f32 v78, v78, 0x3c800000, v201
	v_mul_f32_e32 v76, 0x4f800000, v78
	v_cmp_gt_f32_e32 vcc, 0xf800000, v78
	s_nop 1
	v_cndmask_b32_e32 v78, v78, v76, vcc
	v_sqrt_f32_e32 v76, v78
	s_nop 0
	v_add_u32_e32 v79, -1, v76
	v_add_u32_e32 v80, 1, v76
	v_fma_f32 v81, -v79, v76, v78
	v_fma_f32 v82, -v80, v76, v78
	v_cmp_ge_f32_e64 s[42:43], 0, v81
	s_nop 1
	v_cndmask_b32_e64 v76, v76, v79, s[42:43]
	v_cmp_lt_f32_e64 s[42:43], 0, v82
	s_nop 1
	v_cndmask_b32_e64 v76, v76, v80, s[42:43]
	v_mul_f32_e32 v79, 0x37800000, v76
	v_cndmask_b32_e32 v76, v76, v79, vcc
	v_cmp_class_f32_e32 vcc, v78, v202
	s_nop 1
	v_cndmask_b32_e32 v78, v76, v78, vcc
	v_div_scale_f32 v76, s[42:43], v78, v78, 1.0
	v_rcp_f32_e32 v79, v76
	v_div_scale_f32 v80, vcc, 1.0, v78, 1.0
	v_fma_f32 v81, -v76, v79, 1.0
	v_fmac_f32_e32 v79, v81, v79
	v_mul_f32_e32 v81, v80, v79
	v_fma_f32 v82, -v76, v81, v80
	v_fmac_f32_e32 v81, v82, v79
	v_fma_f32 v76, -v76, v81, v80
	v_div_fmas_f32 v76, v76, v79, v81
	v_div_fixup_f32 v83, v76, v78, 1.0
	v_mul_f32_e32 v92, v72, v83
	v_mul_f32_e32 v92, v60, v92
	v_mul_f32_e32 v92, v88, v92
	v_mul_f32_e32 v93, v73, v83
	v_mul_f32_e32 v93, v61, v93
	v_mul_f32_e32 v93, v89, v93
	v_mul_f32_e32 v94, v74, v83
	v_mul_f32_e32 v94, v62, v94
	v_mul_f32_e32 v94, v90, v94
	v_mul_f32_e32 v95, v75, v83
	v_mul_f32_e32 v95, v63, v95
	v_mul_f32_e32 v95, v91, v95
	v_cvt_pk_bf16_f32 v96, v92, v93
	v_cvt_pk_bf16_f32 v97, v94, v95
	s_lshl_b32 s12, s101, 11
	s_add_u32 s8, s40, s12
	s_addc_u32 s9, s41, 0
	global_store_dwordx2 v65, v[96:97], s[8:9]
	s_mul_i32 s100, s68, 6
	s_add_u32 s100, s100, s101
	s_cmp_le_u32 s100, s71
	s_cselect_b32 s100, s100, s101
	s_lshl_b32 s12, s100, 10
	s_add_u32 s8, s24, s12
	s_addc_u32 s9, s25, 0
	global_load_dwordx4 v[0:3], v64, s[8:9]
	s_add_u32 s8, s36, s12
	s_addc_u32 s9, s37, 0
	global_load_dwordx4 v[4:7], v64, s[8:9]
	s_mul_i32 s12, s100, 0x1600
	s_add_u32 s8, s38, s12
	s_addc_u32 s9, s39, 0
	global_load_dwordx2 v[8:9], v65, s[8:9]
	s_add_u32 s101, s101, s68
	s_cmp_gt_u32 s101, s71
	s_cbranch_scc1 .Lhf_exit
	s_waitcnt vmcnt(16)
	v_add_f32_e32 v72, v10, v14
	v_add_f32_e32 v73, v11, v15
	v_add_f32_e32 v74, v12, v16
	v_add_f32_e32 v75, v13, v17
	v_lshlrev_b32_e32 v84, 16, v18
	v_and_b32_e32 v85, 0xffff0000, v18
	v_lshlrev_b32_e32 v86, 16, v19
	v_and_b32_e32 v87, 0xffff0000, v19
	v_mul_f32_e32 v76, v73, v73
	v_mul_f32_e32 v77, v75, v75
	v_fmac_f32_e32 v76, v72, v72
	v_fmac_f32_e32 v77, v74, v74
	v_add_f32_e32 v78, v76, v77
	ds_bpermute_b32 v76, v67, v78
	v_mul_f32_e32 v88, 0xbfb8aa3b, v84
	v_mul_f32_e32 v89, 0xbfb8aa3b, v85
	v_mul_f32_e32 v90, 0xbfb8aa3b, v86
	v_mul_f32_e32 v91, 0xbfb8aa3b, v87
	s_waitcnt lgkmcnt(0)
	v_add_f32_e32 v78, v78, v76
	ds_bpermute_b32 v76, v68, v78
	v_exp_f32_e32 v88, v88
	v_exp_f32_e32 v89, v89
	v_exp_f32_e32 v90, v90
	v_exp_f32_e32 v91, v91
	s_waitcnt lgkmcnt(0)
	v_add_f32_e32 v78, v78, v76
	ds_bpermute_b32 v76, v69, v78
	v_add_f32_e32 v88, 1.0, v88
	v_add_f32_e32 v89, 1.0, v89
	v_add_f32_e32 v90, 1.0, v90
	v_add_f32_e32 v91, 1.0, v91
	s_waitcnt lgkmcnt(0)
	v_add_f32_e32 v78, v78, v76
	ds_bpermute_b32 v76, v70, v78
	v_rcp_f32_e32 v88, v88
	v_rcp_f32_e32 v89, v89
	v_rcp_f32_e32 v90, v90
	v_rcp_f32_e32 v91, v91
	s_waitcnt lgkmcnt(0)
	v_add_f32_e32 v78, v78, v76
	v_mul_f32_e32 v88, v88, v84
	v_mul_f32_e32 v89, v89, v85
	v_mul_f32_e32 v90, v90, v86
	v_mul_f32_e32 v91, v91, v87
	v_fmamk_f32 v78, v78, 0x3c800000, v201
	v_mul_f32_e32 v76, 0x4f800000, v78
	v_cmp_gt_f32_e32 vcc, 0xf800000, v78
	s_nop 1
	v_cndmask_b32_e32 v78, v78, v76, vcc
	v_sqrt_f32_e32 v76, v78
	s_nop 0
	v_add_u32_e32 v79, -1, v76
	v_add_u32_e32 v80, 1, v76
	v_fma_f32 v81, -v79, v76, v78
	v_fma_f32 v82, -v80, v76, v78
	v_cmp_ge_f32_e64 s[42:43], 0, v81
	s_nop 1
	v_cndmask_b32_e64 v76, v76, v79, s[42:43]
	v_cmp_lt_f32_e64 s[42:43], 0, v82
	s_nop 1
	v_cndmask_b32_e64 v76, v76, v80, s[42:43]
	v_mul_f32_e32 v79, 0x37800000, v76
	v_cndmask_b32_e32 v76, v76, v79, vcc
	v_cmp_class_f32_e32 vcc, v78, v202
	s_nop 1
	v_cndmask_b32_e32 v78, v76, v78, vcc
	v_div_scale_f32 v76, s[42:43], v78, v78, 1.0
	v_rcp_f32_e32 v79, v76
	v_div_scale_f32 v80, vcc, 1.0, v78, 1.0
	v_fma_f32 v81, -v76, v79, 1.0
	v_fmac_f32_e32 v79, v81, v79
	v_mul_f32_e32 v81, v80, v79
	v_fma_f32 v82, -v76, v81, v80
	v_fmac_f32_e32 v81, v82, v79
	v_fma_f32 v76, -v76, v81, v80
	v_div_fmas_f32 v76, v76, v79, v81
	v_div_fixup_f32 v83, v76, v78, 1.0
	v_mul_f32_e32 v92, v72, v83
	v_mul_f32_e32 v92, v60, v92
	v_mul_f32_e32 v92, v88, v92
	v_mul_f32_e32 v93, v73, v83
	v_mul_f32_e32 v93, v61, v93
	v_mul_f32_e32 v93, v89, v93
	v_mul_f32_e32 v94, v74, v83
	v_mul_f32_e32 v94, v62, v94
	v_mul_f32_e32 v94, v90, v94
	v_mul_f32_e32 v95, v75, v83
	v_mul_f32_e32 v95, v63, v95
	v_mul_f32_e32 v95, v91, v95
	v_cvt_pk_bf16_f32 v96, v92, v93
	v_cvt_pk_bf16_f32 v97, v94, v95
	s_lshl_b32 s12, s101, 11
	s_add_u32 s8, s40, s12
	s_addc_u32 s9, s41, 0
	global_store_dwordx2 v65, v[96:97], s[8:9]
	s_mul_i32 s100, s68, 6
	s_add_u32 s100, s100, s101
	s_cmp_le_u32 s100, s71
	s_cselect_b32 s100, s100, s101
	s_lshl_b32 s12, s100, 10
	s_add_u32 s8, s24, s12
	s_addc_u32 s9, s25, 0
	global_load_dwordx4 v[10:13], v64, s[8:9]
	s_add_u32 s8, s36, s12
	s_addc_u32 s9, s37, 0
	global_load_dwordx4 v[14:17], v64, s[8:9]
	s_mul_i32 s12, s100, 0x1600
	s_add_u32 s8, s38, s12
	s_addc_u32 s9, s39, 0
	global_load_dwordx2 v[18:19], v65, s[8:9]
	s_add_u32 s101, s101, s68
	s_cmp_gt_u32 s101, s71
	s_cbranch_scc1 .Lhf_exit
; __device__ __forceinline__ unsigned pk2(float lo, float hi) { f32x2_t v = {lo, hi}; bf16x2_t b = __builtin_convertvector(v, bf16x2_t); return __builtin_bit_cast(unsigned, b); }
; __device__ __forceinline__ float shx(float v, int o, int lane) { return __builtin_bit_cast(float, __builtin_amdgcn_ds_bpermute((lane ^ o) << 2, __builtin_bit_cast(int, v))); }
; __device__ __forceinline__ float sigmoidf_(float z) { return __builtin_amdgcn_rcpf(1.0f + fast_exp2(-z * LOG2E)); }
; __device__ __forceinline__ void phase_hfin(const Params& P, int l) {
;     ...
;     for (long i0 = (long)blockIdx.x * 512 + tid; i0 < total; i0 += 3 * S) {
;         f32x4 a[3], b2[3]; u32x2 gw[3];
; #pragma unroll
;         for (int u = 0; u < 3; ++u) {
;             const long i = i0 + u * S; const bool ok = i < total; const long rh = (ok ? i : i0) >> 4; const int h = (int)(rh & 3); const long r = rh >> 2;
;             const size_t off = (size_t)r * 256 + h * 64 + sub * 4;
;             a[u] = *(const f32x4*)(od0 + off); b2[u] = *(const f32x4*)(od1 + off);
;             gw[u] = *(const u32x2*)(proj + (size_t)r * INW + PB_G + h * 64 + sub * 4);
;         }
; #pragma unroll
;         for (int u = 0; u < 3; ++u) {
;             const long i = i0 + u * S; if (i >= total) break;
;             const long rh = i >> 4; const int h = (int)(rh & 3); const long r = rh >> 2;
;             const f32x4 o = a[u] + b2[u];
;             float ss = (o.x * o.x + o.y * o.y) + (o.z * o.z + o.w * o.w);
;             ss += shx(ss, 1, lane); ss += shx(ss, 2, lane); ss += shx(ss, 4, lane); ss += shx(ss, 8, lane);
;             const float rs = 1.0f / sqrtf(ss * (1.0f / 64.0f) + RMS_EPS);
;             const float g0 = bflo(gw[u].x), g1 = bfhi(gw[u].x), g2 = bflo(gw[u].y), g3 = bfhi(gw[u].y);
;             u32x2 w; w.x = pk2(o.x * rs * gg.x * (g0 * sigmoidf_(g0)), o.y * rs * gg.y * (g1 * sigmoidf_(g1))); w.y = pk2(o.z * rs * gg.z * (g2 * sigmoidf_(g2)), o.w * rs * gg.w * (g3 * sigmoidf_(g3)));
;             *(u32x2*)(mix + (size_t)r * DM + 256 + h * 64 + sub * 4) = w;
;         }
	s_waitcnt vmcnt(17)
	v_add_f32_e32 v72, v20, v24
	v_add_f32_e32 v73, v21, v25
	v_add_f32_e32 v74, v22, v26
	v_add_f32_e32 v75, v23, v27
	v_lshlrev_b32_e32 v84, 16, v28
	v_and_b32_e32 v85, 0xffff0000, v28
	v_lshlrev_b32_e32 v86, 16, v29
	v_and_b32_e32 v87, 0xffff0000, v29
	v_mul_f32_e32 v76, v73, v73
	v_mul_f32_e32 v77, v75, v75
	v_fmac_f32_e32 v76, v72, v72
	v_fmac_f32_e32 v77, v74, v74
	v_add_f32_e32 v78, v76, v77
	ds_bpermute_b32 v76, v67, v78
	v_mul_f32_e32 v88, 0xbfb8aa3b, v84
	v_mul_f32_e32 v89, 0xbfb8aa3b, v85
	v_mul_f32_e32 v90, 0xbfb8aa3b, v86
	v_mul_f32_e32 v91, 0xbfb8aa3b, v87
	s_waitcnt lgkmcnt(0)
	v_add_f32_e32 v78, v78, v76
	ds_bpermute_b32 v76, v68, v78
	v_exp_f32_e32 v88, v88
	v_exp_f32_e32 v89, v89
	v_exp_f32_e32 v90, v90
	v_exp_f32_e32 v91, v91
	s_waitcnt lgkmcnt(0)
	v_add_f32_e32 v78, v78, v76
	ds_bpermute_b32 v76, v69, v78
	v_add_f32_e32 v88, 1.0, v88
	v_add_f32_e32 v89, 1.0, v89
	v_add_f32_e32 v90, 1.0, v90
	v_add_f32_e32 v91, 1.0, v91
	s_waitcnt lgkmcnt(0)
	v_add_f32_e32 v78, v78, v76
	ds_bpermute_b32 v76, v70, v78
	v_rcp_f32_e32 v88, v88
	v_rcp_f32_e32 v89, v89
	v_rcp_f32_e32 v90, v90
	v_rcp_f32_e32 v91, v91
	s_waitcnt lgkmcnt(0)
	v_add_f32_e32 v78, v78, v76
	v_mul_f32_e32 v88, v88, v84
	v_mul_f32_e32 v89, v89, v85
	v_mul_f32_e32 v90, v90, v86
	v_mul_f32_e32 v91, v91, v87
	v_fmamk_f32 v78, v78, 0x3c800000, v201
	v_mul_f32_e32 v76, 0x4f800000, v78
	v_cmp_gt_f32_e32 vcc, 0xf800000, v78
	s_nop 1
	v_cndmask_b32_e32 v78, v78, v76, vcc
	v_sqrt_f32_e32 v76, v78
	s_nop 0
	v_add_u32_e32 v79, -1, v76
	v_add_u32_e32 v80, 1, v76
	v_fma_f32 v81, -v79, v76, v78
	v_fma_f32 v82, -v80, v76, v78
	v_cmp_ge_f32_e64 s[42:43], 0, v81
	s_nop 1
	v_cndmask_b32_e64 v76, v76, v79, s[42:43]
	v_cmp_lt_f32_e64 s[42:43], 0, v82
	s_nop 1
	v_cndmask_b32_e64 v76, v76, v80, s[42:43]
	v_mul_f32_e32 v79, 0x37800000, v76
	v_cndmask_b32_e32 v76, v76, v79, vcc
	v_cmp_class_f32_e32 vcc, v78, v202
	s_nop 1
	v_cndmask_b32_e32 v78, v76, v78, vcc
	v_div_scale_f32 v76, s[42:43], v78, v78, 1.0
	v_rcp_f32_e32 v79, v76
	v_div_scale_f32 v80, vcc, 1.0, v78, 1.0
	v_fma_f32 v81, -v76, v79, 1.0
	v_fmac_f32_e32 v79, v81, v79
	v_mul_f32_e32 v81, v80, v79
	v_fma_f32 v82, -v76, v81, v80
	v_fmac_f32_e32 v81, v82, v79
	v_fma_f32 v76, -v76, v81, v80
	v_div_fmas_f32 v76, v76, v79, v81
	v_div_fixup_f32 v83, v76, v78, 1.0
	v_mul_f32_e32 v92, v72, v83
	v_mul_f32_e32 v92, v60, v92
	v_mul_f32_e32 v92, v88, v92
	v_mul_f32_e32 v93, v73, v83
	v_mul_f32_e32 v93, v61, v93
	v_mul_f32_e32 v93, v89, v93
	v_mul_f32_e32 v94, v74, v83
	v_mul_f32_e32 v94, v62, v94
	v_mul_f32_e32 v94, v90, v94
	v_mul_f32_e32 v95, v75, v83
	v_mul_f32_e32 v95, v63, v95
	v_mul_f32_e32 v95, v91, v95
	v_cvt_pk_bf16_f32 v96, v92, v93
	v_cvt_pk_bf16_f32 v97, v94, v95
	s_lshl_b32 s12, s101, 11
	s_add_u32 s8, s40, s12
	s_addc_u32 s9, s41, 0
	global_store_dwordx2 v65, v[96:97], s[8:9]
	s_mul_i32 s100, s68, 6
	s_add_u32 s100, s100, s101
	s_cmp_le_u32 s100, s71
	s_cselect_b32 s100, s100, s101
	s_lshl_b32 s12, s100, 10
	s_add_u32 s8, s24, s12
	s_addc_u32 s9, s25, 0
	global_load_dwordx4 v[20:23], v64, s[8:9]
	s_add_u32 s8, s36, s12
	s_addc_u32 s9, s37, 0
	global_load_dwordx4 v[24:27], v64, s[8:9]
	s_mul_i32 s12, s100, 0x1600
	s_add_u32 s8, s38, s12
	s_addc_u32 s9, s39, 0
	global_load_dwordx2 v[28:29], v65, s[8:9]
	s_add_u32 s101, s101, s68
	s_cmp_gt_u32 s101, s71
	s_cbranch_scc1 .Lhf_exit
	s_waitcnt vmcnt(18)
	v_add_f32_e32 v72, v30, v34
	v_add_f32_e32 v73, v31, v35
	v_add_f32_e32 v74, v32, v36
	v_add_f32_e32 v75, v33, v37
	v_lshlrev_b32_e32 v84, 16, v38
	v_and_b32_e32 v85, 0xffff0000, v38
	v_lshlrev_b32_e32 v86, 16, v39
	v_and_b32_e32 v87, 0xffff0000, v39
	v_mul_f32_e32 v76, v73, v73
	v_mul_f32_e32 v77, v75, v75
	v_fmac_f32_e32 v76, v72, v72
	v_fmac_f32_e32 v77, v74, v74
	v_add_f32_e32 v78, v76, v77
	ds_bpermute_b32 v76, v67, v78
	v_mul_f32_e32 v88, 0xbfb8aa3b, v84
	v_mul_f32_e32 v89, 0xbfb8aa3b, v85
	v_mul_f32_e32 v90, 0xbfb8aa3b, v86
	v_mul_f32_e32 v91, 0xbfb8aa3b, v87
	s_waitcnt lgkmcnt(0)
	v_add_f32_e32 v78, v78, v76
	ds_bpermute_b32 v76, v68, v78
	v_exp_f32_e32 v88, v88
	v_exp_f32_e32 v89, v89
	v_exp_f32_e32 v90, v90
	v_exp_f32_e32 v91, v91
	s_waitcnt lgkmcnt(0)
	v_add_f32_e32 v78, v78, v76
	ds_bpermute_b32 v76, v69, v78
	v_add_f32_e32 v88, 1.0, v88
	v_add_f32_e32 v89, 1.0, v89
	v_add_f32_e32 v90, 1.0, v90
	v_add_f32_e32 v91, 1.0, v91
	s_waitcnt lgkmcnt(0)
	v_add_f32_e32 v78, v78, v76
	ds_bpermute_b32 v76, v70, v78
	v_rcp_f32_e32 v88, v88
	v_rcp_f32_e32 v89, v89
	v_rcp_f32_e32 v90, v90
	v_rcp_f32_e32 v91, v91
	s_waitcnt lgkmcnt(0)
	v_add_f32_e32 v78, v78, v76
	v_mul_f32_e32 v88, v88, v84
	v_mul_f32_e32 v89, v89, v85
	v_mul_f32_e32 v90, v90, v86
	v_mul_f32_e32 v91, v91, v87
	v_fmamk_f32 v78, v78, 0x3c800000, v201
	v_mul_f32_e32 v76, 0x4f800000, v78
	v_cmp_gt_f32_e32 vcc, 0xf800000, v78
	s_nop 1
	v_cndmask_b32_e32 v78, v78, v76, vcc
	v_sqrt_f32_e32 v76, v78
	s_nop 0
	v_add_u32_e32 v79, -1, v76
	v_add_u32_e32 v80, 1, v76
	v_fma_f32 v81, -v79, v76, v78
	v_fma_f32 v82, -v80, v76, v78
	v_cmp_ge_f32_e64 s[42:43], 0, v81
	s_nop 1
	v_cndmask_b32_e64 v76, v76, v79, s[42:43]
	v_cmp_lt_f32_e64 s[42:43], 0, v82
	s_nop 1
	v_cndmask_b32_e64 v76, v76, v80, s[42:43]
	v_mul_f32_e32 v79, 0x37800000, v76
	v_cndmask_b32_e32 v76, v76, v79, vcc
	v_cmp_class_f32_e32 vcc, v78, v202
	s_nop 1
	v_cndmask_b32_e32 v78, v76, v78, vcc
	v_div_scale_f32 v76, s[42:43], v78, v78, 1.0
	v_rcp_f32_e32 v79, v76
	v_div_scale_f32 v80, vcc, 1.0, v78, 1.0
	v_fma_f32 v81, -v76, v79, 1.0
	v_fmac_f32_e32 v79, v81, v79
	v_mul_f32_e32 v81, v80, v79
	v_fma_f32 v82, -v76, v81, v80
	v_fmac_f32_e32 v81, v82, v79
	v_fma_f32 v76, -v76, v81, v80
	v_div_fmas_f32 v76, v76, v79, v81
	v_div_fixup_f32 v83, v76, v78, 1.0
	v_mul_f32_e32 v92, v72, v83
	v_mul_f32_e32 v92, v60, v92
	v_mul_f32_e32 v92, v88, v92
	v_mul_f32_e32 v93, v73, v83
	v_mul_f32_e32 v93, v61, v93
	v_mul_f32_e32 v93, v89, v93
	v_mul_f32_e32 v94, v74, v83
	v_mul_f32_e32 v94, v62, v94
	v_mul_f32_e32 v94, v90, v94
	v_mul_f32_e32 v95, v75, v83
	v_mul_f32_e32 v95, v63, v95
	v_mul_f32_e32 v95, v91, v95
	v_cvt_pk_bf16_f32 v96, v92, v93
	v_cvt_pk_bf16_f32 v97, v94, v95
	s_lshl_b32 s12, s101, 11
	s_add_u32 s8, s40, s12
	s_addc_u32 s9, s41, 0
	global_store_dwordx2 v65, v[96:97], s[8:9]
	s_mul_i32 s100, s68, 6
	s_add_u32 s100, s100, s101
	s_cmp_le_u32 s100, s71
	s_cselect_b32 s100, s100, s101
	s_lshl_b32 s12, s100, 10
	s_add_u32 s8, s24, s12
	s_addc_u32 s9, s25, 0
	global_load_dwordx4 v[30:33], v64, s[8:9]
	s_add_u32 s8, s36, s12
	s_addc_u32 s9, s37, 0
	global_load_dwordx4 v[34:37], v64, s[8:9]
	s_mul_i32 s12, s100, 0x1600
	s_add_u32 s8, s38, s12
	s_addc_u32 s9, s39, 0
	global_load_dwordx2 v[38:39], v65, s[8:9]
	s_add_u32 s101, s101, s68
	s_cmp_gt_u32 s101, s71
	s_cbranch_scc1 .Lhf_exit
; __device__ __forceinline__ unsigned pk2(float lo, float hi) { f32x2_t v = {lo, hi}; bf16x2_t b = __builtin_convertvector(v, bf16x2_t); return __builtin_bit_cast(unsigned, b); }
; __device__ __forceinline__ float shx(float v, int o, int lane) { return __builtin_bit_cast(float, __builtin_amdgcn_ds_bpermute((lane ^ o) << 2, __builtin_bit_cast(int, v))); }
; __device__ __forceinline__ float sigmoidf_(float z) { return __builtin_amdgcn_rcpf(1.0f + fast_exp2(-z * LOG2E)); }
; __device__ __forceinline__ void phase_hfin(const Params& P, int l) {
;     ...
;     for (long i0 = (long)blockIdx.x * 512 + tid; i0 < total; i0 += 3 * S) {
;         f32x4 a[3], b2[3]; u32x2 gw[3];
; #pragma unroll
;         for (int u = 0; u < 3; ++u) {
;             const long i = i0 + u * S; const bool ok = i < total; const long rh = (ok ? i : i0) >> 4; const int h = (int)(rh & 3); const long r = rh >> 2;
;             const size_t off = (size_t)r * 256 + h * 64 + sub * 4;
;             a[u] = *(const f32x4*)(od0 + off); b2[u] = *(const f32x4*)(od1 + off);
;             gw[u] = *(const u32x2*)(proj + (size_t)r * INW + PB_G + h * 64 + sub * 4);
;         }
; #pragma unroll
;         for (int u = 0; u < 3; ++u) {
;             const long i = i0 + u * S; if (i >= total) break;
;             const long rh = i >> 4; const int h = (int)(rh & 3); const long r = rh >> 2;
;             const f32x4 o = a[u] + b2[u];
;             float ss = (o.x * o.x + o.y * o.y) + (o.z * o.z + o.w * o.w);
;             ss += shx(ss, 1, lane); ss += shx(ss, 2, lane); ss += shx(ss, 4, lane); ss += shx(ss, 8, lane);
;             const float rs = 1.0f / sqrtf(ss * (1.0f / 64.0f) + RMS_EPS);
;             const float g0 = bflo(gw[u].x), g1 = bfhi(gw[u].x), g2 = bflo(gw[u].y), g3 = bfhi(gw[u].y);
;             u32x2 w; w.x = pk2(o.x * rs * gg.x * (g0 * sigmoidf_(g0)), o.y * rs * gg.y * (g1 * sigmoidf_(g1))); w.y = pk2(o.z * rs * gg.z * (g2 * sigmoidf_(g2)), o.w * rs * gg.w * (g3 * sigmoidf_(g3)));
;             *(u32x2*)(mix + (size_t)r * DM + 256 + h * 64 + sub * 4) = w;
;         }
	s_waitcnt vmcnt(19)
	v_add_f32_e32 v72, v40, v44
	v_add_f32_e32 v73, v41, v45
	v_add_f32_e32 v74, v42, v46
	v_add_f32_e32 v75, v43, v47
	v_lshlrev_b32_e32 v84, 16, v48
	v_and_b32_e32 v85, 0xffff0000, v48
	v_lshlrev_b32_e32 v86, 16, v49
	v_and_b32_e32 v87, 0xffff0000, v49
	v_mul_f32_e32 v76, v73, v73
	v_mul_f32_e32 v77, v75, v75
	v_fmac_f32_e32 v76, v72, v72
	v_fmac_f32_e32 v77, v74, v74
	v_add_f32_e32 v78, v76, v77
	ds_bpermute_b32 v76, v67, v78
	v_mul_f32_e32 v88, 0xbfb8aa3b, v84
	v_mul_f32_e32 v89, 0xbfb8aa3b, v85
	v_mul_f32_e32 v90, 0xbfb8aa3b, v86
	v_mul_f32_e32 v91, 0xbfb8aa3b, v87
	s_waitcnt lgkmcnt(0)
	v_add_f32_e32 v78, v78, v76
	ds_bpermute_b32 v76, v68, v78
	v_exp_f32_e32 v88, v88
	v_exp_f32_e32 v89, v89
	v_exp_f32_e32 v90, v90
	v_exp_f32_e32 v91, v91
	s_waitcnt lgkmcnt(0)
	v_add_f32_e32 v78, v78, v76
	ds_bpermute_b32 v76, v69, v78
	v_add_f32_e32 v88, 1.0, v88
	v_add_f32_e32 v89, 1.0, v89
	v_add_f32_e32 v90, 1.0, v90
	v_add_f32_e32 v91, 1.0, v91
	s_waitcnt lgkmcnt(0)
	v_add_f32_e32 v78, v78, v76
	ds_bpermute_b32 v76, v70, v78
	v_rcp_f32_e32 v88, v88
	v_rcp_f32_e32 v89, v89
	v_rcp_f32_e32 v90, v90
	v_rcp_f32_e32 v91, v91
	s_waitcnt lgkmcnt(0)
	v_add_f32_e32 v78, v78, v76
	v_mul_f32_e32 v88, v88, v84
	v_mul_f32_e32 v89, v89, v85
	v_mul_f32_e32 v90, v90, v86
	v_mul_f32_e32 v91, v91, v87
	v_fmamk_f32 v78, v78, 0x3c800000, v201
	v_mul_f32_e32 v76, 0x4f800000, v78
	v_cmp_gt_f32_e32 vcc, 0xf800000, v78
	s_nop 1
	v_cndmask_b32_e32 v78, v78, v76, vcc
	v_sqrt_f32_e32 v76, v78
	s_nop 0
	v_add_u32_e32 v79, -1, v76
	v_add_u32_e32 v80, 1, v76
	v_fma_f32 v81, -v79, v76, v78
	v_fma_f32 v82, -v80, v76, v78
	v_cmp_ge_f32_e64 s[42:43], 0, v81
	s_nop 1
	v_cndmask_b32_e64 v76, v76, v79, s[42:43]
	v_cmp_lt_f32_e64 s[42:43], 0, v82
	s_nop 1
	v_cndmask_b32_e64 v76, v76, v80, s[42:43]
	v_mul_f32_e32 v79, 0x37800000, v76
	v_cndmask_b32_e32 v76, v76, v79, vcc
	v_cmp_class_f32_e32 vcc, v78, v202
	s_nop 1
	v_cndmask_b32_e32 v78, v76, v78, vcc
	v_div_scale_f32 v76, s[42:43], v78, v78, 1.0
	v_rcp_f32_e32 v79, v76
	v_div_scale_f32 v80, vcc, 1.0, v78, 1.0
	v_fma_f32 v81, -v76, v79, 1.0
	v_fmac_f32_e32 v79, v81, v79
	v_mul_f32_e32 v81, v80, v79
	v_fma_f32 v82, -v76, v81, v80
	v_fmac_f32_e32 v81, v82, v79
	v_fma_f32 v76, -v76, v81, v80
	v_div_fmas_f32 v76, v76, v79, v81
	v_div_fixup_f32 v83, v76, v78, 1.0
	v_mul_f32_e32 v92, v72, v83
	v_mul_f32_e32 v92, v60, v92
	v_mul_f32_e32 v92, v88, v92
	v_mul_f32_e32 v93, v73, v83
	v_mul_f32_e32 v93, v61, v93
	v_mul_f32_e32 v93, v89, v93
	v_mul_f32_e32 v94, v74, v83
	v_mul_f32_e32 v94, v62, v94
	v_mul_f32_e32 v94, v90, v94
	v_mul_f32_e32 v95, v75, v83
	v_mul_f32_e32 v95, v63, v95
	v_mul_f32_e32 v95, v91, v95
	v_cvt_pk_bf16_f32 v96, v92, v93
	v_cvt_pk_bf16_f32 v97, v94, v95
	s_lshl_b32 s12, s101, 11
	s_add_u32 s8, s40, s12
	s_addc_u32 s9, s41, 0
	global_store_dwordx2 v65, v[96:97], s[8:9]
	s_mul_i32 s100, s68, 6
	s_add_u32 s100, s100, s101
	s_cmp_le_u32 s100, s71
	s_cselect_b32 s100, s100, s101
	s_lshl_b32 s12, s100, 10
	s_add_u32 s8, s24, s12
	s_addc_u32 s9, s25, 0
	global_load_dwordx4 v[40:43], v64, s[8:9]
	s_add_u32 s8, s36, s12
	s_addc_u32 s9, s37, 0
	global_load_dwordx4 v[44:47], v64, s[8:9]
	s_mul_i32 s12, s100, 0x1600
	s_add_u32 s8, s38, s12
	s_addc_u32 s9, s39, 0
	global_load_dwordx2 v[48:49], v65, s[8:9]
	s_add_u32 s101, s101, s68
	s_cmp_gt_u32 s101, s71
	s_cbranch_scc1 .Lhf_exit
	s_waitcnt vmcnt(20)
	v_add_f32_e32 v72, v50, v54
	v_add_f32_e32 v73, v51, v55
	v_add_f32_e32 v74, v52, v56
	v_add_f32_e32 v75, v53, v57
	v_lshlrev_b32_e32 v84, 16, v58
	v_and_b32_e32 v85, 0xffff0000, v58
	v_lshlrev_b32_e32 v86, 16, v59
	v_and_b32_e32 v87, 0xffff0000, v59
	v_mul_f32_e32 v76, v73, v73
	v_mul_f32_e32 v77, v75, v75
	v_fmac_f32_e32 v76, v72, v72
	v_fmac_f32_e32 v77, v74, v74
	v_add_f32_e32 v78, v76, v77
	ds_bpermute_b32 v76, v67, v78
	v_mul_f32_e32 v88, 0xbfb8aa3b, v84
	v_mul_f32_e32 v89, 0xbfb8aa3b, v85
	v_mul_f32_e32 v90, 0xbfb8aa3b, v86
	v_mul_f32_e32 v91, 0xbfb8aa3b, v87
	s_waitcnt lgkmcnt(0)
	v_add_f32_e32 v78, v78, v76
	ds_bpermute_b32 v76, v68, v78
	v_exp_f32_e32 v88, v88
	v_exp_f32_e32 v89, v89
	v_exp_f32_e32 v90, v90
	v_exp_f32_e32 v91, v91
	s_waitcnt lgkmcnt(0)
	v_add_f32_e32 v78, v78, v76
	ds_bpermute_b32 v76, v69, v78
	v_add_f32_e32 v88, 1.0, v88
	v_add_f32_e32 v89, 1.0, v89
	v_add_f32_e32 v90, 1.0, v90
	v_add_f32_e32 v91, 1.0, v91
	s_waitcnt lgkmcnt(0)
	v_add_f32_e32 v78, v78, v76
	ds_bpermute_b32 v76, v70, v78
	v_rcp_f32_e32 v88, v88
	v_rcp_f32_e32 v89, v89
	v_rcp_f32_e32 v90, v90
	v_rcp_f32_e32 v91, v91
	s_waitcnt lgkmcnt(0)
	v_add_f32_e32 v78, v78, v76
	v_mul_f32_e32 v88, v88, v84
	v_mul_f32_e32 v89, v89, v85
	v_mul_f32_e32 v90, v90, v86
	v_mul_f32_e32 v91, v91, v87
	v_fmamk_f32 v78, v78, 0x3c800000, v201
	v_mul_f32_e32 v76, 0x4f800000, v78
	v_cmp_gt_f32_e32 vcc, 0xf800000, v78
	s_nop 1
	v_cndmask_b32_e32 v78, v78, v76, vcc
	v_sqrt_f32_e32 v76, v78
	s_nop 0
	v_add_u32_e32 v79, -1, v76
	v_add_u32_e32 v80, 1, v76
	v_fma_f32 v81, -v79, v76, v78
	v_fma_f32 v82, -v80, v76, v78
	v_cmp_ge_f32_e64 s[42:43], 0, v81
	s_nop 1
	v_cndmask_b32_e64 v76, v76, v79, s[42:43]
	v_cmp_lt_f32_e64 s[42:43], 0, v82
	s_nop 1
	v_cndmask_b32_e64 v76, v76, v80, s[42:43]
	v_mul_f32_e32 v79, 0x37800000, v76
	v_cndmask_b32_e32 v76, v76, v79, vcc
	v_cmp_class_f32_e32 vcc, v78, v202
	s_nop 1
	v_cndmask_b32_e32 v78, v76, v78, vcc
	v_div_scale_f32 v76, s[42:43], v78, v78, 1.0
	v_rcp_f32_e32 v79, v76
	v_div_scale_f32 v80, vcc, 1.0, v78, 1.0
	v_fma_f32 v81, -v76, v79, 1.0
	v_fmac_f32_e32 v79, v81, v79
	v_mul_f32_e32 v81, v80, v79
	v_fma_f32 v82, -v76, v81, v80
	v_fmac_f32_e32 v81, v82, v79
	v_fma_f32 v76, -v76, v81, v80
	v_div_fmas_f32 v76, v76, v79, v81
	v_div_fixup_f32 v83, v76, v78, 1.0
	v_mul_f32_e32 v92, v72, v83
	v_mul_f32_e32 v92, v60, v92
	v_mul_f32_e32 v92, v88, v92
	v_mul_f32_e32 v93, v73, v83
	v_mul_f32_e32 v93, v61, v93
	v_mul_f32_e32 v93, v89, v93
	v_mul_f32_e32 v94, v74, v83
	v_mul_f32_e32 v94, v62, v94
	v_mul_f32_e32 v94, v90, v94
	v_mul_f32_e32 v95, v75, v83
	v_mul_f32_e32 v95, v63, v95
	v_mul_f32_e32 v95, v91, v95
	v_cvt_pk_bf16_f32 v96, v92, v93
	v_cvt_pk_bf16_f32 v97, v94, v95
	s_lshl_b32 s12, s101, 11
	s_add_u32 s8, s40, s12
	s_addc_u32 s9, s41, 0
	global_store_dwordx2 v65, v[96:97], s[8:9]
	s_mul_i32 s100, s68, 6
	s_add_u32 s100, s100, s101
	s_cmp_le_u32 s100, s71
	s_cselect_b32 s100, s100, s101
	s_lshl_b32 s12, s100, 10
	s_add_u32 s8, s24, s12
	s_addc_u32 s9, s25, 0
	global_load_dwordx4 v[50:53], v64, s[8:9]
	s_add_u32 s8, s36, s12
	s_addc_u32 s9, s37, 0
	global_load_dwordx4 v[54:57], v64, s[8:9]
	s_mul_i32 s12, s100, 0x1600
	s_add_u32 s8, s38, s12
	s_addc_u32 s9, s39, 0
	global_load_dwordx2 v[58:59], v65, s[8:9]
	s_add_u32 s101, s101, s68
	s_cmp_gt_u32 s101, s71
	s_cbranch_scc1 .Lhf_exit
; __device__ __forceinline__ unsigned pk2(float lo, float hi) { f32x2_t v = {lo, hi}; bf16x2_t b = __builtin_convertvector(v, bf16x2_t); return __builtin_bit_cast(unsigned, b); }
; __device__ __forceinline__ float shx(float v, int o, int lane) { return __builtin_bit_cast(float, __builtin_amdgcn_ds_bpermute((lane ^ o) << 2, __builtin_bit_cast(int, v))); }
; __device__ __forceinline__ float sigmoidf_(float z) { return __builtin_amdgcn_rcpf(1.0f + fast_exp2(-z * LOG2E)); }
; __device__ __forceinline__ void phase_hfin(const Params& P, int l) {
;     ...
;     for (long i0 = (long)blockIdx.x * 512 + tid; i0 < total; i0 += 3 * S) {
;         f32x4 a[3], b2[3]; u32x2 gw[3];
; #pragma unroll
;         for (int u = 0; u < 3; ++u) {
;             const long i = i0 + u * S; const bool ok = i < total; const long rh = (ok ? i : i0) >> 4; const int h = (int)(rh & 3); const long r = rh >> 2;
;             const size_t off = (size_t)r * 256 + h * 64 + sub * 4;
;             a[u] = *(const f32x4*)(od0 + off); b2[u] = *(const f32x4*)(od1 + off);
;             gw[u] = *(const u32x2*)(proj + (size_t)r * INW + PB_G + h * 64 + sub * 4);
;         }
; #pragma unroll
;         for (int u = 0; u < 3; ++u) {
;             const long i = i0 + u * S; if (i >= total) break;
;             const long rh = i >> 4; const int h = (int)(rh & 3); const long r = rh >> 2;
;             const f32x4 o = a[u] + b2[u];
;             float ss = (o.x * o.x + o.y * o.y) + (o.z * o.z + o.w * o.w);
;             ss += shx(ss, 1, lane); ss += shx(ss, 2, lane); ss += shx(ss, 4, lane); ss += shx(ss, 8, lane);
;             const float rs = 1.0f / sqrtf(ss * (1.0f / 64.0f) + RMS_EPS);
;             const float g0 = bflo(gw[u].x), g1 = bfhi(gw[u].x), g2 = bflo(gw[u].y), g3 = bfhi(gw[u].y);
;             u32x2 w; w.x = pk2(o.x * rs * gg.x * (g0 * sigmoidf_(g0)), o.y * rs * gg.y * (g1 * sigmoidf_(g1))); w.y = pk2(o.z * rs * gg.z * (g2 * sigmoidf_(g2)), o.w * rs * gg.w * (g3 * sigmoidf_(g3)));
;             *(u32x2*)(mix + (size_t)r * DM + 256 + h * 64 + sub * 4) = w;
;         }
.Lhf_loop:
	s_waitcnt vmcnt(20)
	v_add_f32_e32 v72, v0, v4
	v_add_f32_e32 v73, v1, v5
	v_add_f32_e32 v74, v2, v6
	v_add_f32_e32 v75, v3, v7
	v_lshlrev_b32_e32 v84, 16, v8
	v_and_b32_e32 v85, 0xffff0000, v8
	v_lshlrev_b32_e32 v86, 16, v9
	v_and_b32_e32 v87, 0xffff0000, v9
	v_mul_f32_e32 v76, v73, v73
	v_mul_f32_e32 v77, v75, v75
	v_fmac_f32_e32 v76, v72, v72
	v_fmac_f32_e32 v77, v74, v74
	v_add_f32_e32 v78, v76, v77
	ds_bpermute_b32 v76, v67, v78
	v_mul_f32_e32 v88, 0xbfb8aa3b, v84
	v_mul_f32_e32 v89, 0xbfb8aa3b, v85
	v_mul_f32_e32 v90, 0xbfb8aa3b, v86
	v_mul_f32_e32 v91, 0xbfb8aa3b, v87
	s_waitcnt lgkmcnt(0)
	v_add_f32_e32 v78, v78, v76
	ds_bpermute_b32 v76, v68, v78
	v_exp_f32_e32 v88, v88
	v_exp_f32_e32 v89, v89
	v_exp_f32_e32 v90, v90
	v_exp_f32_e32 v91, v91
	s_waitcnt lgkmcnt(0)
	v_add_f32_e32 v78, v78, v76
	ds_bpermute_b32 v76, v69, v78
	v_add_f32_e32 v88, 1.0, v88
	v_add_f32_e32 v89, 1.0, v89
	v_add_f32_e32 v90, 1.0, v90
	v_add_f32_e32 v91, 1.0, v91
	s_waitcnt lgkmcnt(0)
	v_add_f32_e32 v78, v78, v76
	ds_bpermute_b32 v76, v70, v78
	v_rcp_f32_e32 v88, v88
	v_rcp_f32_e32 v89, v89
	v_rcp_f32_e32 v90, v90
	v_rcp_f32_e32 v91, v91
	s_waitcnt lgkmcnt(0)
	v_add_f32_e32 v78, v78, v76
	v_mul_f32_e32 v88, v88, v84
	v_mul_f32_e32 v89, v89, v85
	v_mul_f32_e32 v90, v90, v86
	v_mul_f32_e32 v91, v91, v87
	v_fmamk_f32 v78, v78, 0x3c800000, v201
	v_mul_f32_e32 v76, 0x4f800000, v78
	v_cmp_gt_f32_e32 vcc, 0xf800000, v78
	s_nop 1
	v_cndmask_b32_e32 v78, v78, v76, vcc
	v_sqrt_f32_e32 v76, v78
	s_nop 0
	v_add_u32_e32 v79, -1, v76
	v_add_u32_e32 v80, 1, v76
	v_fma_f32 v81, -v79, v76, v78
	v_fma_f32 v82, -v80, v76, v78
	v_cmp_ge_f32_e64 s[42:43], 0, v81
	s_nop 1
	v_cndmask_b32_e64 v76, v76, v79, s[42:43]
	v_cmp_lt_f32_e64 s[42:43], 0, v82
	s_nop 1
	v_cndmask_b32_e64 v76, v76, v80, s[42:43]
	v_mul_f32_e32 v79, 0x37800000, v76
	v_cndmask_b32_e32 v76, v76, v79, vcc
	v_cmp_class_f32_e32 vcc, v78, v202
	s_nop 1
	v_cndmask_b32_e32 v78, v76, v78, vcc
	v_div_scale_f32 v76, s[42:43], v78, v78, 1.0
	v_rcp_f32_e32 v79, v76
	v_div_scale_f32 v80, vcc, 1.0, v78, 1.0
	v_fma_f32 v81, -v76, v79, 1.0
	v_fmac_f32_e32 v79, v81, v79
	v_mul_f32_e32 v81, v80, v79
	v_fma_f32 v82, -v76, v81, v80
	v_fmac_f32_e32 v81, v82, v79
	v_fma_f32 v76, -v76, v81, v80
	v_div_fmas_f32 v76, v76, v79, v81
	v_div_fixup_f32 v83, v76, v78, 1.0
	v_mul_f32_e32 v92, v72, v83
	v_mul_f32_e32 v92, v60, v92
	v_mul_f32_e32 v92, v88, v92
	v_mul_f32_e32 v93, v73, v83
	v_mul_f32_e32 v93, v61, v93
	v_mul_f32_e32 v93, v89, v93
	v_mul_f32_e32 v94, v74, v83
	v_mul_f32_e32 v94, v62, v94
	v_mul_f32_e32 v94, v90, v94
	v_mul_f32_e32 v95, v75, v83
	v_mul_f32_e32 v95, v63, v95
	v_mul_f32_e32 v95, v91, v95
	v_cvt_pk_bf16_f32 v96, v92, v93
	v_cvt_pk_bf16_f32 v97, v94, v95
	s_lshl_b32 s12, s101, 11
	s_add_u32 s8, s40, s12
	s_addc_u32 s9, s41, 0
	global_store_dwordx2 v65, v[96:97], s[8:9]
	s_mul_i32 s100, s68, 6
	s_add_u32 s100, s100, s101
	s_cmp_le_u32 s100, s71
	s_cselect_b32 s100, s100, s101
	s_lshl_b32 s12, s100, 10
	s_add_u32 s8, s24, s12
	s_addc_u32 s9, s25, 0
	global_load_dwordx4 v[0:3], v64, s[8:9]
	s_add_u32 s8, s36, s12
	s_addc_u32 s9, s37, 0
	global_load_dwordx4 v[4:7], v64, s[8:9]
	s_mul_i32 s12, s100, 0x1600
	s_add_u32 s8, s38, s12
	s_addc_u32 s9, s39, 0
	global_load_dwordx2 v[8:9], v65, s[8:9]
	s_add_u32 s101, s101, s68
	s_cmp_gt_u32 s101, s71
	s_cbranch_scc1 .Lhf_exit
	s_waitcnt vmcnt(20)
	v_add_f32_e32 v72, v10, v14
	v_add_f32_e32 v73, v11, v15
	v_add_f32_e32 v74, v12, v16
	v_add_f32_e32 v75, v13, v17
	v_lshlrev_b32_e32 v84, 16, v18
	v_and_b32_e32 v85, 0xffff0000, v18
	v_lshlrev_b32_e32 v86, 16, v19
	v_and_b32_e32 v87, 0xffff0000, v19
	v_mul_f32_e32 v76, v73, v73
	v_mul_f32_e32 v77, v75, v75
	v_fmac_f32_e32 v76, v72, v72
	v_fmac_f32_e32 v77, v74, v74
	v_add_f32_e32 v78, v76, v77
	ds_bpermute_b32 v76, v67, v78
	v_mul_f32_e32 v88, 0xbfb8aa3b, v84
	v_mul_f32_e32 v89, 0xbfb8aa3b, v85
	v_mul_f32_e32 v90, 0xbfb8aa3b, v86
	v_mul_f32_e32 v91, 0xbfb8aa3b, v87
	s_waitcnt lgkmcnt(0)
	v_add_f32_e32 v78, v78, v76
	ds_bpermute_b32 v76, v68, v78
	v_exp_f32_e32 v88, v88
	v_exp_f32_e32 v89, v89
	v_exp_f32_e32 v90, v90
	v_exp_f32_e32 v91, v91
	s_waitcnt lgkmcnt(0)
	v_add_f32_e32 v78, v78, v76
	ds_bpermute_b32 v76, v69, v78
	v_add_f32_e32 v88, 1.0, v88
	v_add_f32_e32 v89, 1.0, v89
	v_add_f32_e32 v90, 1.0, v90
	v_add_f32_e32 v91, 1.0, v91
	s_waitcnt lgkmcnt(0)
	v_add_f32_e32 v78, v78, v76
	ds_bpermute_b32 v76, v70, v78
	v_rcp_f32_e32 v88, v88
	v_rcp_f32_e32 v89, v89
	v_rcp_f32_e32 v90, v90
	v_rcp_f32_e32 v91, v91
	s_waitcnt lgkmcnt(0)
	v_add_f32_e32 v78, v78, v76
	v_mul_f32_e32 v88, v88, v84
	v_mul_f32_e32 v89, v89, v85
	v_mul_f32_e32 v90, v90, v86
	v_mul_f32_e32 v91, v91, v87
	v_fmamk_f32 v78, v78, 0x3c800000, v201
	v_mul_f32_e32 v76, 0x4f800000, v78
	v_cmp_gt_f32_e32 vcc, 0xf800000, v78
	s_nop 1
	v_cndmask_b32_e32 v78, v78, v76, vcc
	v_sqrt_f32_e32 v76, v78
	s_nop 0
	v_add_u32_e32 v79, -1, v76
	v_add_u32_e32 v80, 1, v76
	v_fma_f32 v81, -v79, v76, v78
	v_fma_f32 v82, -v80, v76, v78
	v_cmp_ge_f32_e64 s[42:43], 0, v81
	s_nop 1
	v_cndmask_b32_e64 v76, v76, v79, s[42:43]
	v_cmp_lt_f32_e64 s[42:43], 0, v82
	s_nop 1
	v_cndmask_b32_e64 v76, v76, v80, s[42:43]
	v_mul_f32_e32 v79, 0x37800000, v76
	v_cndmask_b32_e32 v76, v76, v79, vcc
	v_cmp_class_f32_e32 vcc, v78, v202
	s_nop 1
	v_cndmask_b32_e32 v78, v76, v78, vcc
	v_div_scale_f32 v76, s[42:43], v78, v78, 1.0
	v_rcp_f32_e32 v79, v76
	v_div_scale_f32 v80, vcc, 1.0, v78, 1.0
	v_fma_f32 v81, -v76, v79, 1.0
	v_fmac_f32_e32 v79, v81, v79
	v_mul_f32_e32 v81, v80, v79
	v_fma_f32 v82, -v76, v81, v80
	v_fmac_f32_e32 v81, v82, v79
	v_fma_f32 v76, -v76, v81, v80
	v_div_fmas_f32 v76, v76, v79, v81
	v_div_fixup_f32 v83, v76, v78, 1.0
	v_mul_f32_e32 v92, v72, v83
	v_mul_f32_e32 v92, v60, v92
	v_mul_f32_e32 v92, v88, v92
	v_mul_f32_e32 v93, v73, v83
	v_mul_f32_e32 v93, v61, v93
	v_mul_f32_e32 v93, v89, v93
	v_mul_f32_e32 v94, v74, v83
	v_mul_f32_e32 v94, v62, v94
	v_mul_f32_e32 v94, v90, v94
	v_mul_f32_e32 v95, v75, v83
	v_mul_f32_e32 v95, v63, v95
	v_mul_f32_e32 v95, v91, v95
	v_cvt_pk_bf16_f32 v96, v92, v93
	v_cvt_pk_bf16_f32 v97, v94, v95
	s_lshl_b32 s12, s101, 11
	s_add_u32 s8, s40, s12
	s_addc_u32 s9, s41, 0
	global_store_dwordx2 v65, v[96:97], s[8:9]
	s_mul_i32 s100, s68, 6
	s_add_u32 s100, s100, s101
	s_cmp_le_u32 s100, s71
	s_cselect_b32 s100, s100, s101
	s_lshl_b32 s12, s100, 10
	s_add_u32 s8, s24, s12
	s_addc_u32 s9, s25, 0
	global_load_dwordx4 v[10:13], v64, s[8:9]
	s_add_u32 s8, s36, s12
	s_addc_u32 s9, s37, 0
	global_load_dwordx4 v[14:17], v64, s[8:9]
	s_mul_i32 s12, s100, 0x1600
	s_add_u32 s8, s38, s12
	s_addc_u32 s9, s39, 0
	global_load_dwordx2 v[18:19], v65, s[8:9]
	s_add_u32 s101, s101, s68
	s_cmp_gt_u32 s101, s71
	s_cbranch_scc1 .Lhf_exit
; __device__ __forceinline__ unsigned pk2(float lo, float hi) { f32x2_t v = {lo, hi}; bf16x2_t b = __builtin_convertvector(v, bf16x2_t); return __builtin_bit_cast(unsigned, b); }
; __device__ __forceinline__ float shx(float v, int o, int lane) { return __builtin_bit_cast(float, __builtin_amdgcn_ds_bpermute((lane ^ o) << 2, __builtin_bit_cast(int, v))); }
; __device__ __forceinline__ float sigmoidf_(float z) { return __builtin_amdgcn_rcpf(1.0f + fast_exp2(-z * LOG2E)); }
; __device__ __forceinline__ void phase_hfin(const Params& P, int l) {
;     ...
;     for (long i0 = (long)blockIdx.x * 512 + tid; i0 < total; i0 += 3 * S) {
;         f32x4 a[3], b2[3]; u32x2 gw[3];
; #pragma unroll
;         for (int u = 0; u < 3; ++u) {
;             const long i = i0 + u * S; const bool ok = i < total; const long rh = (ok ? i : i0) >> 4; const int h = (int)(rh & 3); const long r = rh >> 2;
;             const size_t off = (size_t)r * 256 + h * 64 + sub * 4;
;             a[u] = *(const f32x4*)(od0 + off); b2[u] = *(const f32x4*)(od1 + off);
;             gw[u] = *(const u32x2*)(proj + (size_t)r * INW + PB_G + h * 64 + sub * 4);
;         }
; #pragma unroll
;         for (int u = 0; u < 3; ++u) {
;             const long i = i0 + u * S; if (i >= total) break;
;             const long rh = i >> 4; const int h = (int)(rh & 3); const long r = rh >> 2;
;             const f32x4 o = a[u] + b2[u];
;             float ss = (o.x * o.x + o.y * o.y) + (o.z * o.z + o.w * o.w);
;             ss += shx(ss, 1, lane); ss += shx(ss, 2, lane); ss += shx(ss, 4, lane); ss += shx(ss, 8, lane);
;             const float rs = 1.0f / sqrtf(ss * (1.0f / 64.0f) + RMS_EPS);
;             const float g0 = bflo(gw[u].x), g1 = bfhi(gw[u].x), g2 = bflo(gw[u].y), g3 = bfhi(gw[u].y);
;             u32x2 w; w.x = pk2(o.x * rs * gg.x * (g0 * sigmoidf_(g0)), o.y * rs * gg.y * (g1 * sigmoidf_(g1))); w.y = pk2(o.z * rs * gg.z * (g2 * sigmoidf_(g2)), o.w * rs * gg.w * (g3 * sigmoidf_(g3)));
;             *(u32x2*)(mix + (size_t)r * DM + 256 + h * 64 + sub * 4) = w;
;         }
	s_waitcnt vmcnt(20)
	v_add_f32_e32 v72, v20, v24
	v_add_f32_e32 v73, v21, v25
	v_add_f32_e32 v74, v22, v26
	v_add_f32_e32 v75, v23, v27
	v_lshlrev_b32_e32 v84, 16, v28
	v_and_b32_e32 v85, 0xffff0000, v28
	v_lshlrev_b32_e32 v86, 16, v29
	v_and_b32_e32 v87, 0xffff0000, v29
	v_mul_f32_e32 v76, v73, v73
	v_mul_f32_e32 v77, v75, v75
	v_fmac_f32_e32 v76, v72, v72
	v_fmac_f32_e32 v77, v74, v74
	v_add_f32_e32 v78, v76, v77
	ds_bpermute_b32 v76, v67, v78
	v_mul_f32_e32 v88, 0xbfb8aa3b, v84
	v_mul_f32_e32 v89, 0xbfb8aa3b, v85
	v_mul_f32_e32 v90, 0xbfb8aa3b, v86
	v_mul_f32_e32 v91, 0xbfb8aa3b, v87
	s_waitcnt lgkmcnt(0)
	v_add_f32_e32 v78, v78, v76
	ds_bpermute_b32 v76, v68, v78
	v_exp_f32_e32 v88, v88
	v_exp_f32_e32 v89, v89
	v_exp_f32_e32 v90, v90
	v_exp_f32_e32 v91, v91
	s_waitcnt lgkmcnt(0)
	v_add_f32_e32 v78, v78, v76
	ds_bpermute_b32 v76, v69, v78
	v_add_f32_e32 v88, 1.0, v88
	v_add_f32_e32 v89, 1.0, v89
	v_add_f32_e32 v90, 1.0, v90
	v_add_f32_e32 v91, 1.0, v91
	s_waitcnt lgkmcnt(0)
	v_add_f32_e32 v78, v78, v76
	ds_bpermute_b32 v76, v70, v78
	v_rcp_f32_e32 v88, v88
	v_rcp_f32_e32 v89, v89
	v_rcp_f32_e32 v90, v90
	v_rcp_f32_e32 v91, v91
	s_waitcnt lgkmcnt(0)
	v_add_f32_e32 v78, v78, v76
	v_mul_f32_e32 v88, v88, v84
	v_mul_f32_e32 v89, v89, v85
	v_mul_f32_e32 v90, v90, v86
	v_mul_f32_e32 v91, v91, v87
	v_fmamk_f32 v78, v78, 0x3c800000, v201
	v_mul_f32_e32 v76, 0x4f800000, v78
	v_cmp_gt_f32_e32 vcc, 0xf800000, v78
	s_nop 1
	v_cndmask_b32_e32 v78, v78, v76, vcc
	v_sqrt_f32_e32 v76, v78
	s_nop 0
	v_add_u32_e32 v79, -1, v76
	v_add_u32_e32 v80, 1, v76
	v_fma_f32 v81, -v79, v76, v78
	v_fma_f32 v82, -v80, v76, v78
	v_cmp_ge_f32_e64 s[42:43], 0, v81
	s_nop 1
	v_cndmask_b32_e64 v76, v76, v79, s[42:43]
	v_cmp_lt_f32_e64 s[42:43], 0, v82
	s_nop 1
	v_cndmask_b32_e64 v76, v76, v80, s[42:43]
	v_mul_f32_e32 v79, 0x37800000, v76
	v_cndmask_b32_e32 v76, v76, v79, vcc
	v_cmp_class_f32_e32 vcc, v78, v202
	s_nop 1
	v_cndmask_b32_e32 v78, v76, v78, vcc
	v_div_scale_f32 v76, s[42:43], v78, v78, 1.0
	v_rcp_f32_e32 v79, v76
	v_div_scale_f32 v80, vcc, 1.0, v78, 1.0
	v_fma_f32 v81, -v76, v79, 1.0
	v_fmac_f32_e32 v79, v81, v79
	v_mul_f32_e32 v81, v80, v79
	v_fma_f32 v82, -v76, v81, v80
	v_fmac_f32_e32 v81, v82, v79
	v_fma_f32 v76, -v76, v81, v80
	v_div_fmas_f32 v76, v76, v79, v81
	v_div_fixup_f32 v83, v76, v78, 1.0
	v_mul_f32_e32 v92, v72, v83
	v_mul_f32_e32 v92, v60, v92
	v_mul_f32_e32 v92, v88, v92
	v_mul_f32_e32 v93, v73, v83
	v_mul_f32_e32 v93, v61, v93
	v_mul_f32_e32 v93, v89, v93
	v_mul_f32_e32 v94, v74, v83
	v_mul_f32_e32 v94, v62, v94
	v_mul_f32_e32 v94, v90, v94
	v_mul_f32_e32 v95, v75, v83
	v_mul_f32_e32 v95, v63, v95
	v_mul_f32_e32 v95, v91, v95
	v_cvt_pk_bf16_f32 v96, v92, v93
	v_cvt_pk_bf16_f32 v97, v94, v95
	s_lshl_b32 s12, s101, 11
	s_add_u32 s8, s40, s12
	s_addc_u32 s9, s41, 0
	global_store_dwordx2 v65, v[96:97], s[8:9]
	s_mul_i32 s100, s68, 6
	s_add_u32 s100, s100, s101
	s_cmp_le_u32 s100, s71
	s_cselect_b32 s100, s100, s101
	s_lshl_b32 s12, s100, 10
	s_add_u32 s8, s24, s12
	s_addc_u32 s9, s25, 0
	global_load_dwordx4 v[20:23], v64, s[8:9]
	s_add_u32 s8, s36, s12
	s_addc_u32 s9, s37, 0
	global_load_dwordx4 v[24:27], v64, s[8:9]
	s_mul_i32 s12, s100, 0x1600
	s_add_u32 s8, s38, s12
	s_addc_u32 s9, s39, 0
	global_load_dwordx2 v[28:29], v65, s[8:9]
	s_add_u32 s101, s101, s68
	s_cmp_gt_u32 s101, s71
	s_cbranch_scc1 .Lhf_exit
	s_waitcnt vmcnt(20)
	v_add_f32_e32 v72, v30, v34
	v_add_f32_e32 v73, v31, v35
	v_add_f32_e32 v74, v32, v36
	v_add_f32_e32 v75, v33, v37
	v_lshlrev_b32_e32 v84, 16, v38
	v_and_b32_e32 v85, 0xffff0000, v38
	v_lshlrev_b32_e32 v86, 16, v39
	v_and_b32_e32 v87, 0xffff0000, v39
	v_mul_f32_e32 v76, v73, v73
	v_mul_f32_e32 v77, v75, v75
	v_fmac_f32_e32 v76, v72, v72
	v_fmac_f32_e32 v77, v74, v74
	v_add_f32_e32 v78, v76, v77
	ds_bpermute_b32 v76, v67, v78
	v_mul_f32_e32 v88, 0xbfb8aa3b, v84
	v_mul_f32_e32 v89, 0xbfb8aa3b, v85
	v_mul_f32_e32 v90, 0xbfb8aa3b, v86
	v_mul_f32_e32 v91, 0xbfb8aa3b, v87
	s_waitcnt lgkmcnt(0)
	v_add_f32_e32 v78, v78, v76
	ds_bpermute_b32 v76, v68, v78
	v_exp_f32_e32 v88, v88
	v_exp_f32_e32 v89, v89
	v_exp_f32_e32 v90, v90
	v_exp_f32_e32 v91, v91
	s_waitcnt lgkmcnt(0)
	v_add_f32_e32 v78, v78, v76
	ds_bpermute_b32 v76, v69, v78
	v_add_f32_e32 v88, 1.0, v88
	v_add_f32_e32 v89, 1.0, v89
	v_add_f32_e32 v90, 1.0, v90
	v_add_f32_e32 v91, 1.0, v91
	s_waitcnt lgkmcnt(0)
	v_add_f32_e32 v78, v78, v76
	ds_bpermute_b32 v76, v70, v78
	v_rcp_f32_e32 v88, v88
	v_rcp_f32_e32 v89, v89
	v_rcp_f32_e32 v90, v90
	v_rcp_f32_e32 v91, v91
	s_waitcnt lgkmcnt(0)
	v_add_f32_e32 v78, v78, v76
	v_mul_f32_e32 v88, v88, v84
	v_mul_f32_e32 v89, v89, v85
	v_mul_f32_e32 v90, v90, v86
	v_mul_f32_e32 v91, v91, v87
	v_fmamk_f32 v78, v78, 0x3c800000, v201
	v_mul_f32_e32 v76, 0x4f800000, v78
	v_cmp_gt_f32_e32 vcc, 0xf800000, v78
	s_nop 1
	v_cndmask_b32_e32 v78, v78, v76, vcc
	v_sqrt_f32_e32 v76, v78
	s_nop 0
	v_add_u32_e32 v79, -1, v76
	v_add_u32_e32 v80, 1, v76
	v_fma_f32 v81, -v79, v76, v78
	v_fma_f32 v82, -v80, v76, v78
	v_cmp_ge_f32_e64 s[42:43], 0, v81
	s_nop 1
	v_cndmask_b32_e64 v76, v76, v79, s[42:43]
	v_cmp_lt_f32_e64 s[42:43], 0, v82
	s_nop 1
	v_cndmask_b32_e64 v76, v76, v80, s[42:43]
	v_mul_f32_e32 v79, 0x37800000, v76
	v_cndmask_b32_e32 v76, v76, v79, vcc
	v_cmp_class_f32_e32 vcc, v78, v202
	s_nop 1
	v_cndmask_b32_e32 v78, v76, v78, vcc
	v_div_scale_f32 v76, s[42:43], v78, v78, 1.0
	v_rcp_f32_e32 v79, v76
	v_div_scale_f32 v80, vcc, 1.0, v78, 1.0
	v_fma_f32 v81, -v76, v79, 1.0
	v_fmac_f32_e32 v79, v81, v79
	v_mul_f32_e32 v81, v80, v79
	v_fma_f32 v82, -v76, v81, v80
	v_fmac_f32_e32 v81, v82, v79
	v_fma_f32 v76, -v76, v81, v80
	v_div_fmas_f32 v76, v76, v79, v81
	v_div_fixup_f32 v83, v76, v78, 1.0
	v_mul_f32_e32 v92, v72, v83
	v_mul_f32_e32 v92, v60, v92
	v_mul_f32_e32 v92, v88, v92
	v_mul_f32_e32 v93, v73, v83
	v_mul_f32_e32 v93, v61, v93
	v_mul_f32_e32 v93, v89, v93
	v_mul_f32_e32 v94, v74, v83
	v_mul_f32_e32 v94, v62, v94
	v_mul_f32_e32 v94, v90, v94
	v_mul_f32_e32 v95, v75, v83
	v_mul_f32_e32 v95, v63, v95
	v_mul_f32_e32 v95, v91, v95
	v_cvt_pk_bf16_f32 v96, v92, v93
	v_cvt_pk_bf16_f32 v97, v94, v95
	s_lshl_b32 s12, s101, 11
	s_add_u32 s8, s40, s12
	s_addc_u32 s9, s41, 0
	global_store_dwordx2 v65, v[96:97], s[8:9]
	s_mul_i32 s100, s68, 6
	s_add_u32 s100, s100, s101
	s_cmp_le_u32 s100, s71
	s_cselect_b32 s100, s100, s101
	s_lshl_b32 s12, s100, 10
	s_add_u32 s8, s24, s12
	s_addc_u32 s9, s25, 0
	global_load_dwordx4 v[30:33], v64, s[8:9]
	s_add_u32 s8, s36, s12
	s_addc_u32 s9, s37, 0
	global_load_dwordx4 v[34:37], v64, s[8:9]
	s_mul_i32 s12, s100, 0x1600
	s_add_u32 s8, s38, s12
	s_addc_u32 s9, s39, 0
	global_load_dwordx2 v[38:39], v65, s[8:9]
	s_add_u32 s101, s101, s68
	s_cmp_gt_u32 s101, s71
	s_cbranch_scc1 .Lhf_exit
; __device__ __forceinline__ unsigned pk2(float lo, float hi) { f32x2_t v = {lo, hi}; bf16x2_t b = __builtin_convertvector(v, bf16x2_t); return __builtin_bit_cast(unsigned, b); }
; __device__ __forceinline__ float shx(float v, int o, int lane) { return __builtin_bit_cast(float, __builtin_amdgcn_ds_bpermute((lane ^ o) << 2, __builtin_bit_cast(int, v))); }
; __device__ __forceinline__ float sigmoidf_(float z) { return __builtin_amdgcn_rcpf(1.0f + fast_exp2(-z * LOG2E)); }
; __device__ __forceinline__ void phase_hfin(const Params& P, int l) {
;     ...
;     for (long i0 = (long)blockIdx.x * 512 + tid; i0 < total; i0 += 3 * S) {
;         f32x4 a[3], b2[3]; u32x2 gw[3];
; #pragma unroll
;         for (int u = 0; u < 3; ++u) {
;             const long i = i0 + u * S; const bool ok = i < total; const long rh = (ok ? i : i0) >> 4; const int h = (int)(rh & 3); const long r = rh >> 2;
;             const size_t off = (size_t)r * 256 + h * 64 + sub * 4;
;             a[u] = *(const f32x4*)(od0 + off); b2[u] = *(const f32x4*)(od1 + off);
;             gw[u] = *(const u32x2*)(proj + (size_t)r * INW + PB_G + h * 64 + sub * 4);
;         }
; #pragma unroll
;         for (int u = 0; u < 3; ++u) {
;             const long i = i0 + u * S; if (i >= total) break;
;             const long rh = i >> 4; const int h = (int)(rh & 3); const long r = rh >> 2;
;             const f32x4 o = a[u] + b2[u];
;             float ss = (o.x * o.x + o.y * o.y) + (o.z * o.z + o.w * o.w);
;             ss += shx(ss, 1, lane); ss += shx(ss, 2, lane); ss += shx(ss, 4, lane); ss += shx(ss, 8, lane);
;             const float rs = 1.0f / sqrtf(ss * (1.0f / 64.0f) + RMS_EPS);
;             const float g0 = bflo(gw[u].x), g1 = bfhi(gw[u].x), g2 = bflo(gw[u].y), g3 = bfhi(gw[u].y);
;             u32x2 w; w.x = pk2(o.x * rs * gg.x * (g0 * sigmoidf_(g0)), o.y * rs * gg.y * (g1 * sigmoidf_(g1))); w.y = pk2(o.z * rs * gg.z * (g2 * sigmoidf_(g2)), o.w * rs * gg.w * (g3 * sigmoidf_(g3)));
;             *(u32x2*)(mix + (size_t)r * DM + 256 + h * 64 + sub * 4) = w;
;         }
;     }
	s_waitcnt vmcnt(20)
	v_add_f32_e32 v72, v40, v44
	v_add_f32_e32 v73, v41, v45
	v_add_f32_e32 v74, v42, v46
	v_add_f32_e32 v75, v43, v47
	v_lshlrev_b32_e32 v84, 16, v48
	v_and_b32_e32 v85, 0xffff0000, v48
	v_lshlrev_b32_e32 v86, 16, v49
	v_and_b32_e32 v87, 0xffff0000, v49
	v_mul_f32_e32 v76, v73, v73
	v_mul_f32_e32 v77, v75, v75
	v_fmac_f32_e32 v76, v72, v72
	v_fmac_f32_e32 v77, v74, v74
	v_add_f32_e32 v78, v76, v77
	ds_bpermute_b32 v76, v67, v78
	v_mul_f32_e32 v88, 0xbfb8aa3b, v84
	v_mul_f32_e32 v89, 0xbfb8aa3b, v85
	v_mul_f32_e32 v90, 0xbfb8aa3b, v86
	v_mul_f32_e32 v91, 0xbfb8aa3b, v87
	s_waitcnt lgkmcnt(0)
	v_add_f32_e32 v78, v78, v76
	ds_bpermute_b32 v76, v68, v78
	v_exp_f32_e32 v88, v88
	v_exp_f32_e32 v89, v89
	v_exp_f32_e32 v90, v90
	v_exp_f32_e32 v91, v91
	s_waitcnt lgkmcnt(0)
	v_add_f32_e32 v78, v78, v76
	ds_bpermute_b32 v76, v69, v78
	v_add_f32_e32 v88, 1.0, v88
	v_add_f32_e32 v89, 1.0, v89
	v_add_f32_e32 v90, 1.0, v90
	v_add_f32_e32 v91, 1.0, v91
	s_waitcnt lgkmcnt(0)
	v_add_f32_e32 v78, v78, v76
	ds_bpermute_b32 v76, v70, v78
	v_rcp_f32_e32 v88, v88
	v_rcp_f32_e32 v89, v89
	v_rcp_f32_e32 v90, v90
	v_rcp_f32_e32 v91, v91
	s_waitcnt lgkmcnt(0)
	v_add_f32_e32 v78, v78, v76
	v_mul_f32_e32 v88, v88, v84
	v_mul_f32_e32 v89, v89, v85
	v_mul_f32_e32 v90, v90, v86
	v_mul_f32_e32 v91, v91, v87
	v_fmamk_f32 v78, v78, 0x3c800000, v201
	v_mul_f32_e32 v76, 0x4f800000, v78
	v_cmp_gt_f32_e32 vcc, 0xf800000, v78
	s_nop 1
	v_cndmask_b32_e32 v78, v78, v76, vcc
	v_sqrt_f32_e32 v76, v78
	s_nop 0
	v_add_u32_e32 v79, -1, v76
	v_add_u32_e32 v80, 1, v76
	v_fma_f32 v81, -v79, v76, v78
	v_fma_f32 v82, -v80, v76, v78
	v_cmp_ge_f32_e64 s[42:43], 0, v81
	s_nop 1
	v_cndmask_b32_e64 v76, v76, v79, s[42:43]
	v_cmp_lt_f32_e64 s[42:43], 0, v82
	s_nop 1
	v_cndmask_b32_e64 v76, v76, v80, s[42:43]
	v_mul_f32_e32 v79, 0x37800000, v76
	v_cndmask_b32_e32 v76, v76, v79, vcc
	v_cmp_class_f32_e32 vcc, v78, v202
	s_nop 1
	v_cndmask_b32_e32 v78, v76, v78, vcc
	v_div_scale_f32 v76, s[42:43], v78, v78, 1.0
	v_rcp_f32_e32 v79, v76
	v_div_scale_f32 v80, vcc, 1.0, v78, 1.0
	v_fma_f32 v81, -v76, v79, 1.0
	v_fmac_f32_e32 v79, v81, v79
	v_mul_f32_e32 v81, v80, v79
	v_fma_f32 v82, -v76, v81, v80
	v_fmac_f32_e32 v81, v82, v79
	v_fma_f32 v76, -v76, v81, v80
	v_div_fmas_f32 v76, v76, v79, v81
	v_div_fixup_f32 v83, v76, v78, 1.0
	v_mul_f32_e32 v92, v72, v83
	v_mul_f32_e32 v92, v60, v92
	v_mul_f32_e32 v92, v88, v92
	v_mul_f32_e32 v93, v73, v83
	v_mul_f32_e32 v93, v61, v93
	v_mul_f32_e32 v93, v89, v93
	v_mul_f32_e32 v94, v74, v83
	v_mul_f32_e32 v94, v62, v94
	v_mul_f32_e32 v94, v90, v94
	v_mul_f32_e32 v95, v75, v83
	v_mul_f32_e32 v95, v63, v95
	v_mul_f32_e32 v95, v91, v95
	v_cvt_pk_bf16_f32 v96, v92, v93
	v_cvt_pk_bf16_f32 v97, v94, v95
	s_lshl_b32 s12, s101, 11
	s_add_u32 s8, s40, s12
	s_addc_u32 s9, s41, 0
	global_store_dwordx2 v65, v[96:97], s[8:9]
	s_mul_i32 s100, s68, 6
	s_add_u32 s100, s100, s101
	s_cmp_le_u32 s100, s71
	s_cselect_b32 s100, s100, s101
	s_lshl_b32 s12, s100, 10
	s_add_u32 s8, s24, s12
	s_addc_u32 s9, s25, 0
	global_load_dwordx4 v[40:43], v64, s[8:9]
	s_add_u32 s8, s36, s12
	s_addc_u32 s9, s37, 0
	global_load_dwordx4 v[44:47], v64, s[8:9]
	s_mul_i32 s12, s100, 0x1600
	s_add_u32 s8, s38, s12
	s_addc_u32 s9, s39, 0
	global_load_dwordx2 v[48:49], v65, s[8:9]
	s_add_u32 s101, s101, s68
	s_cmp_gt_u32 s101, s71
	s_cbranch_scc1 .Lhf_exit
	s_waitcnt vmcnt(20)
	v_add_f32_e32 v72, v50, v54
	v_add_f32_e32 v73, v51, v55
	v_add_f32_e32 v74, v52, v56
	v_add_f32_e32 v75, v53, v57
	v_lshlrev_b32_e32 v84, 16, v58
	v_and_b32_e32 v85, 0xffff0000, v58
	v_lshlrev_b32_e32 v86, 16, v59
	v_and_b32_e32 v87, 0xffff0000, v59
	v_mul_f32_e32 v76, v73, v73
	v_mul_f32_e32 v77, v75, v75
	v_fmac_f32_e32 v76, v72, v72
	v_fmac_f32_e32 v77, v74, v74
	v_add_f32_e32 v78, v76, v77
	ds_bpermute_b32 v76, v67, v78
	v_mul_f32_e32 v88, 0xbfb8aa3b, v84
	v_mul_f32_e32 v89, 0xbfb8aa3b, v85
	v_mul_f32_e32 v90, 0xbfb8aa3b, v86
	v_mul_f32_e32 v91, 0xbfb8aa3b, v87
	s_waitcnt lgkmcnt(0)
	v_add_f32_e32 v78, v78, v76
	ds_bpermute_b32 v76, v68, v78
	v_exp_f32_e32 v88, v88
	v_exp_f32_e32 v89, v89
	v_exp_f32_e32 v90, v90
	v_exp_f32_e32 v91, v91
	s_waitcnt lgkmcnt(0)
	v_add_f32_e32 v78, v78, v76
	ds_bpermute_b32 v76, v69, v78
	v_add_f32_e32 v88, 1.0, v88
	v_add_f32_e32 v89, 1.0, v89
	v_add_f32_e32 v90, 1.0, v90
	v_add_f32_e32 v91, 1.0, v91
	s_waitcnt lgkmcnt(0)
	v_add_f32_e32 v78, v78, v76
	ds_bpermute_b32 v76, v70, v78
	v_rcp_f32_e32 v88, v88
	v_rcp_f32_e32 v89, v89
	v_rcp_f32_e32 v90, v90
	v_rcp_f32_e32 v91, v91
	s_waitcnt lgkmcnt(0)
	v_add_f32_e32 v78, v78, v76
	v_mul_f32_e32 v88, v88, v84
	v_mul_f32_e32 v89, v89, v85
	v_mul_f32_e32 v90, v90, v86
	v_mul_f32_e32 v91, v91, v87
	v_fmamk_f32 v78, v78, 0x3c800000, v201
	v_mul_f32_e32 v76, 0x4f800000, v78
	v_cmp_gt_f32_e32 vcc, 0xf800000, v78
	s_nop 1
	v_cndmask_b32_e32 v78, v78, v76, vcc
	v_sqrt_f32_e32 v76, v78
	s_nop 0
	v_add_u32_e32 v79, -1, v76
	v_add_u32_e32 v80, 1, v76
	v_fma_f32 v81, -v79, v76, v78
	v_fma_f32 v82, -v80, v76, v78
	v_cmp_ge_f32_e64 s[42:43], 0, v81
	s_nop 1
	v_cndmask_b32_e64 v76, v76, v79, s[42:43]
	v_cmp_lt_f32_e64 s[42:43], 0, v82
	s_nop 1
	v_cndmask_b32_e64 v76, v76, v80, s[42:43]
	v_mul_f32_e32 v79, 0x37800000, v76
	v_cndmask_b32_e32 v76, v76, v79, vcc
	v_cmp_class_f32_e32 vcc, v78, v202
	s_nop 1
	v_cndmask_b32_e32 v78, v76, v78, vcc
	v_div_scale_f32 v76, s[42:43], v78, v78, 1.0
	v_rcp_f32_e32 v79, v76
	v_div_scale_f32 v80, vcc, 1.0, v78, 1.0
	v_fma_f32 v81, -v76, v79, 1.0
	v_fmac_f32_e32 v79, v81, v79
	v_mul_f32_e32 v81, v80, v79
	v_fma_f32 v82, -v76, v81, v80
	v_fmac_f32_e32 v81, v82, v79
	v_fma_f32 v76, -v76, v81, v80
	v_div_fmas_f32 v76, v76, v79, v81
	v_div_fixup_f32 v83, v76, v78, 1.0
	v_mul_f32_e32 v92, v72, v83
	v_mul_f32_e32 v92, v60, v92
	v_mul_f32_e32 v92, v88, v92
	v_mul_f32_e32 v93, v73, v83
	v_mul_f32_e32 v93, v61, v93
	v_mul_f32_e32 v93, v89, v93
	v_mul_f32_e32 v94, v74, v83
	v_mul_f32_e32 v94, v62, v94
	v_mul_f32_e32 v94, v90, v94
	v_mul_f32_e32 v95, v75, v83
	v_mul_f32_e32 v95, v63, v95
	v_mul_f32_e32 v95, v91, v95
	v_cvt_pk_bf16_f32 v96, v92, v93
	v_cvt_pk_bf16_f32 v97, v94, v95
	s_lshl_b32 s12, s101, 11
	s_add_u32 s8, s40, s12
	s_addc_u32 s9, s41, 0
	global_store_dwordx2 v65, v[96:97], s[8:9]
	s_mul_i32 s100, s68, 6
	s_add_u32 s100, s100, s101
	s_cmp_le_u32 s100, s71
	s_cselect_b32 s100, s100, s101
	s_lshl_b32 s12, s100, 10
	s_add_u32 s8, s24, s12
	s_addc_u32 s9, s25, 0
	global_load_dwordx4 v[50:53], v64, s[8:9]
	s_add_u32 s8, s36, s12
	s_addc_u32 s9, s37, 0
	global_load_dwordx4 v[54:57], v64, s[8:9]
	s_mul_i32 s12, s100, 0x1600
	s_add_u32 s8, s38, s12
	s_addc_u32 s9, s39, 0
	global_load_dwordx2 v[58:59], v65, s[8:9]
	s_add_u32 s101, s101, s68
	s_cmp_gt_u32 s101, s71
	s_cbranch_scc1 .Lhf_exit
	s_branch .Lhf_loop
.Lhf_exit:
	s_waitcnt vmcnt(0)
	s_mov_b64 s[44:45], 0

; __device__ __forceinline__ int opaque_tid() { int t = threadIdx.x; asm volatile("" : "+v"(t)); return t; }
; __device__ __forceinline__ void phase_final(const Params& P) {
;     const int tid = opaque_tid(), lane = tid & 63, wave = tid >> 6;
;     const int gw = blockIdx.x * 8 + wave, NGW = gridDim.x * 8;
;     for (int r = gw; r < NBATCH * SEQ; r += NGW) {
;         float* xr = P.out + (size_t)r * DM;
;         f32x4 v[4]; float s2 = 0.f;
; #pragma unroll
;         for (int j = 0; j < 4; ++j) { v[j] = *((const f32x4*)xr + lane + 64 * j); s2 += (v[j].x * v[j].x + v[j].y * v[j].y) + (v[j].z * v[j].z + v[j].w * v[j].w); }
;         const float rstd = 1.0f / sqrtf(wave_sum(s2, lane) * (1.0f / DM) + RMS_EPS);
; #pragma unroll
;         for (int j = 0; j < 4; ++j) { const f32x4 g = *((const f32x4*)P.final_norm + lane + 64 * j); *((f32x4*)xr + lane + 64 * j) = v[j] * rstd * g; }
;     }
; }
.LBB0_1217:
	v_readfirstlane_b32 s8, v2
	v_readfirstlane_b32 s9, v3
	v_readfirstlane_b32 s10, v4
	v_readfirstlane_b32 s11, v5
	v_readfirstlane_b32 s12, v0
	s_nop 3
	v_subrev_u32_e32 v161, s8, v2
	v_lshrrev_b32_e32 v146, 2, v161
	v_mov_b32_e32 v154, 0x358637bd
	v_mov_b32_e32 v155, 0x260
	v_xor_b32_e32 v162, 4, v146
	v_xor_b32_e32 v163, 8, v146
	v_xor_b32_e32 v164, 16, v146
	v_xor_b32_e32 v165, 32, v146
	v_xor_b32_e32 v166, 64, v146
	v_xor_b32_e32 v167, 0x80, v146
	s_sub_u32 s10, s10, 0xc00
	s_subb_u32 s11, s11, 0
	global_load_dwordx4 v[112:115], v161, s[8:9]
	global_load_dwordx4 v[116:119], v161, s[8:9] offset:1024
	global_load_dwordx4 v[120:123], v161, s[8:9] offset:2048
	global_load_dwordx4 v[124:127], v161, s[8:9] offset:3072
	s_mov_b32 s14, s10
	s_mov_b32 s15, s11
	global_load_dwordx4 v[64:67], v161, s[14:15]
	global_load_dwordx4 v[68:71], v161, s[14:15] offset:1024
	global_load_dwordx4 v[72:75], v161, s[14:15] offset:2048
	global_load_dwordx4 v[76:79], v161, s[14:15] offset:3072
	s_mul_i32 s13, s68, 1
	s_add_u32 s13, s13, s12
	s_mul_i32 s16, s2, 1
	s_cmp_le_u32 s13, 0x7fff
	s_cselect_b32 s16, s16, 0
	s_add_u32 s14, s10, s16
	s_addc_u32 s15, s11, 0
	global_load_dwordx4 v[80:83], v161, s[14:15]
	global_load_dwordx4 v[84:87], v161, s[14:15] offset:1024
	global_load_dwordx4 v[88:91], v161, s[14:15] offset:2048
	global_load_dwordx4 v[92:95], v161, s[14:15] offset:3072
	s_mul_i32 s13, s68, 2
	s_add_u32 s13, s13, s12
	s_mul_i32 s16, s2, 2
	s_cmp_le_u32 s13, 0x7fff
	s_cselect_b32 s16, s16, 0
	s_add_u32 s14, s10, s16
	s_addc_u32 s15, s11, 0
	global_load_dwordx4 v[96:99], v161, s[14:15]
	global_load_dwordx4 v[100:103], v161, s[14:15] offset:1024
	global_load_dwordx4 v[104:107], v161, s[14:15] offset:2048
	global_load_dwordx4 v[108:111], v161, s[14:15] offset:3072
	s_waitcnt vmcnt(8)
	v_mul_f32_e32 v146, v65, v65
	v_mul_f32_e32 v147, v67, v67
	v_fmac_f32_e32 v146, v64, v64
	v_fmac_f32_e32 v147, v66, v66
	v_add_f32_e32 v148, v146, v147
	v_mul_f32_e32 v146, v69, v69
	v_mul_f32_e32 v147, v71, v71
	v_fmac_f32_e32 v146, v68, v68
	v_fmac_f32_e32 v147, v70, v70
	v_add_f32_e32 v146, v146, v147
	v_add_f32_e32 v148, v148, v146
	v_mul_f32_e32 v146, v73, v73
	v_mul_f32_e32 v147, v75, v75
	v_fmac_f32_e32 v146, v72, v72
	v_fmac_f32_e32 v147, v74, v74
	v_add_f32_e32 v146, v146, v147
	v_add_f32_e32 v148, v148, v146
	v_mul_f32_e32 v146, v77, v77
	v_mul_f32_e32 v147, v79, v79
	v_fmac_f32_e32 v146, v76, v76
	v_fmac_f32_e32 v147, v78, v78
	v_add_f32_e32 v146, v146, v147
	v_add_f32_e32 v148, v148, v146
	ds_bpermute_b32 v146, v162, v148
	s_waitcnt lgkmcnt(0)
	v_add_f32_e32 v148, v148, v146
	ds_bpermute_b32 v146, v163, v148
	s_waitcnt lgkmcnt(0)
	v_add_f32_e32 v148, v148, v146
	ds_bpermute_b32 v146, v164, v148
	s_waitcnt lgkmcnt(0)
	v_add_f32_e32 v148, v148, v146
	ds_bpermute_b32 v146, v165, v148
	s_waitcnt lgkmcnt(0)
	v_add_f32_e32 v148, v148, v146
	ds_bpermute_b32 v146, v166, v148
	s_waitcnt lgkmcnt(0)
	v_add_f32_e32 v148, v148, v146
	ds_bpermute_b32 v146, v167, v148
	s_waitcnt lgkmcnt(0)
	v_add_f32_e32 v148, v148, v146
	v_fmamk_f32 v148, v148, 0x3a800000, v154
	v_mul_f32_e32 v146, 0x4f800000, v148
	v_cmp_gt_f32_e32 vcc, 0xf800000, v148
	s_nop 1
	v_cndmask_b32_e32 v148, v148, v146, vcc
	v_sqrt_f32_e32 v146, v148
	s_nop 0
	v_add_u32_e32 v149, -1, v146
	v_add_u32_e32 v150, 1, v146
	v_fma_f32 v151, -v149, v146, v148
	v_fma_f32 v152, -v150, v146, v148
	v_cmp_ge_f32_e64 s[18:19], 0, v151
	s_nop 1
	v_cndmask_b32_e64 v146, v146, v149, s[18:19]
	v_cmp_lt_f32_e64 s[18:19], 0, v152
	s_nop 1
	v_cndmask_b32_e64 v146, v146, v150, s[18:19]
	v_mul_f32_e32 v149, 0x37800000, v146
	v_cndmask_b32_e32 v146, v146, v149, vcc
	v_cmp_class_f32_e32 vcc, v148, v155
	s_nop 1
	v_cndmask_b32_e32 v148, v146, v148, vcc
	v_div_scale_f32 v146, s[18:19], v148, v148, 1.0
	v_rcp_f32_e32 v149, v146
	v_div_scale_f32 v150, vcc, 1.0, v148, 1.0
	v_fma_f32 v151, -v146, v149, 1.0
	v_fmac_f32_e32 v149, v151, v149
	v_mul_f32_e32 v151, v150, v149
	v_fma_f32 v152, -v146, v151, v150
	v_fmac_f32_e32 v151, v152, v149
	v_fma_f32 v146, -v146, v151, v150
	v_div_fmas_f32 v146, v146, v149, v151
	v_div_fixup_f32 v153, v146, v148, 1.0
	v_mul_f32_e32 v130, v64, v153
	v_mul_f32_e32 v130, v112, v130
	v_mul_f32_e32 v131, v65, v153
	v_mul_f32_e32 v131, v113, v131
	v_mul_f32_e32 v132, v66, v153
	v_mul_f32_e32 v132, v114, v132
	v_mul_f32_e32 v133, v67, v153
	v_mul_f32_e32 v133, v115, v133
	global_store_dwordx4 v161, v[130:133], s[10:11]
	v_mul_f32_e32 v134, v68, v153
	v_mul_f32_e32 v134, v116, v134
	v_mul_f32_e32 v135, v69, v153
	v_mul_f32_e32 v135, v117, v135
	v_mul_f32_e32 v136, v70, v153
	v_mul_f32_e32 v136, v118, v136
	v_mul_f32_e32 v137, v71, v153
	v_mul_f32_e32 v137, v119, v137
	global_store_dwordx4 v161, v[134:137], s[10:11] offset:1024
	v_mul_f32_e32 v138, v72, v153
	v_mul_f32_e32 v138, v120, v138
	v_mul_f32_e32 v139, v73, v153
	v_mul_f32_e32 v139, v121, v139
	v_mul_f32_e32 v140, v74, v153
	v_mul_f32_e32 v140, v122, v140
	v_mul_f32_e32 v141, v75, v153
	v_mul_f32_e32 v141, v123, v141
	global_store_dwordx4 v161, v[138:141], s[10:11] offset:2048
	v_mul_f32_e32 v142, v76, v153
	v_mul_f32_e32 v142, v124, v142
	v_mul_f32_e32 v143, v77, v153
	v_mul_f32_e32 v143, v125, v143
	v_mul_f32_e32 v144, v78, v153
	v_mul_f32_e32 v144, v126, v144
	v_mul_f32_e32 v145, v79, v153
	v_mul_f32_e32 v145, v127, v145
	global_store_dwordx4 v161, v[142:145], s[10:11] offset:3072
	s_mul_i32 s13, s68, 3
	s_add_u32 s13, s13, s12
	s_mul_i32 s16, s2, 3
	s_cmp_le_u32 s13, 0x7fff
	s_cselect_b32 s16, s16, 0
	s_add_u32 s14, s10, s16
	s_addc_u32 s15, s11, 0
	global_load_dwordx4 v[64:67], v161, s[14:15]
	global_load_dwordx4 v[68:71], v161, s[14:15] offset:1024
	global_load_dwordx4 v[72:75], v161, s[14:15] offset:2048
	global_load_dwordx4 v[76:79], v161, s[14:15] offset:3072
	s_add_u32 s12, s12, s68
	s_add_u32 s10, s10, s2
	s_addc_u32 s11, s11, s3
	s_cmp_gt_u32 s12, 0x7fff
	s_cbranch_scc1 .Lnf_fin_exit
; __device__ __forceinline__ void phase_final(const Params& P) {
;     ...
;     for (int r = gw; r < NBATCH * SEQ; r += NGW) {
;         float* xr = P.out + (size_t)r * DM;
;         f32x4 v[4]; float s2 = 0.f;
; #pragma unroll
;         for (int j = 0; j < 4; ++j) { v[j] = *((const f32x4*)xr + lane + 64 * j); s2 += (v[j].x * v[j].x + v[j].y * v[j].y) + (v[j].z * v[j].z + v[j].w * v[j].w); }
;         const float rstd = 1.0f / sqrtf(wave_sum(s2, lane) * (1.0f / DM) + RMS_EPS);
; #pragma unroll
;         for (int j = 0; j < 4; ++j) { const f32x4 g = *((const f32x4*)P.final_norm + lane + 64 * j); *((f32x4*)xr + lane + 64 * j) = v[j] * rstd * g; }
;     }
	s_waitcnt vmcnt(12)
	v_mul_f32_e32 v146, v81, v81
	v_mul_f32_e32 v147, v83, v83
	v_fmac_f32_e32 v146, v80, v80
	v_fmac_f32_e32 v147, v82, v82
	v_add_f32_e32 v148, v146, v147
	v_mul_f32_e32 v146, v85, v85
	v_mul_f32_e32 v147, v87, v87
	v_fmac_f32_e32 v146, v84, v84
	v_fmac_f32_e32 v147, v86, v86
	v_add_f32_e32 v146, v146, v147
	v_add_f32_e32 v148, v148, v146
	v_mul_f32_e32 v146, v89, v89
	v_mul_f32_e32 v147, v91, v91
	v_fmac_f32_e32 v146, v88, v88
	v_fmac_f32_e32 v147, v90, v90
	v_add_f32_e32 v146, v146, v147
	v_add_f32_e32 v148, v148, v146
	v_mul_f32_e32 v146, v93, v93
	v_mul_f32_e32 v147, v95, v95
	v_fmac_f32_e32 v146, v92, v92
	v_fmac_f32_e32 v147, v94, v94
	v_add_f32_e32 v146, v146, v147
	v_add_f32_e32 v148, v148, v146
	ds_bpermute_b32 v146, v162, v148
	s_waitcnt lgkmcnt(0)
	v_add_f32_e32 v148, v148, v146
	ds_bpermute_b32 v146, v163, v148
	s_waitcnt lgkmcnt(0)
	v_add_f32_e32 v148, v148, v146
	ds_bpermute_b32 v146, v164, v148
	s_waitcnt lgkmcnt(0)
	v_add_f32_e32 v148, v148, v146
	ds_bpermute_b32 v146, v165, v148
	s_waitcnt lgkmcnt(0)
	v_add_f32_e32 v148, v148, v146
	ds_bpermute_b32 v146, v166, v148
	s_waitcnt lgkmcnt(0)
	v_add_f32_e32 v148, v148, v146
	ds_bpermute_b32 v146, v167, v148
	s_waitcnt lgkmcnt(0)
	v_add_f32_e32 v148, v148, v146
	v_fmamk_f32 v148, v148, 0x3a800000, v154
	v_mul_f32_e32 v146, 0x4f800000, v148
	v_cmp_gt_f32_e32 vcc, 0xf800000, v148
	s_nop 1
	v_cndmask_b32_e32 v148, v148, v146, vcc
	v_sqrt_f32_e32 v146, v148
	s_nop 0
	v_add_u32_e32 v149, -1, v146
	v_add_u32_e32 v150, 1, v146
	v_fma_f32 v151, -v149, v146, v148
	v_fma_f32 v152, -v150, v146, v148
	v_cmp_ge_f32_e64 s[18:19], 0, v151
	s_nop 1
	v_cndmask_b32_e64 v146, v146, v149, s[18:19]
	v_cmp_lt_f32_e64 s[18:19], 0, v152
	s_nop 1
	v_cndmask_b32_e64 v146, v146, v150, s[18:19]
	v_mul_f32_e32 v149, 0x37800000, v146
	v_cndmask_b32_e32 v146, v146, v149, vcc
	v_cmp_class_f32_e32 vcc, v148, v155
	s_nop 1
	v_cndmask_b32_e32 v148, v146, v148, vcc
	v_div_scale_f32 v146, s[18:19], v148, v148, 1.0
	v_rcp_f32_e32 v149, v146
	v_div_scale_f32 v150, vcc, 1.0, v148, 1.0
	v_fma_f32 v151, -v146, v149, 1.0
	v_fmac_f32_e32 v149, v151, v149
	v_mul_f32_e32 v151, v150, v149
	v_fma_f32 v152, -v146, v151, v150
	v_fmac_f32_e32 v151, v152, v149
	v_fma_f32 v146, -v146, v151, v150
	v_div_fmas_f32 v146, v146, v149, v151
	v_div_fixup_f32 v153, v146, v148, 1.0
	v_mul_f32_e32 v130, v80, v153
	v_mul_f32_e32 v130, v112, v130
	v_mul_f32_e32 v131, v81, v153
	v_mul_f32_e32 v131, v113, v131
	v_mul_f32_e32 v132, v82, v153
	v_mul_f32_e32 v132, v114, v132
	v_mul_f32_e32 v133, v83, v153
	v_mul_f32_e32 v133, v115, v133
	global_store_dwordx4 v161, v[130:133], s[10:11]
	v_mul_f32_e32 v134, v84, v153
	v_mul_f32_e32 v134, v116, v134
	v_mul_f32_e32 v135, v85, v153
	v_mul_f32_e32 v135, v117, v135
	v_mul_f32_e32 v136, v86, v153
	v_mul_f32_e32 v136, v118, v136
	v_mul_f32_e32 v137, v87, v153
	v_mul_f32_e32 v137, v119, v137
	global_store_dwordx4 v161, v[134:137], s[10:11] offset:1024
	v_mul_f32_e32 v138, v88, v153
	v_mul_f32_e32 v138, v120, v138
	v_mul_f32_e32 v139, v89, v153
	v_mul_f32_e32 v139, v121, v139
	v_mul_f32_e32 v140, v90, v153
	v_mul_f32_e32 v140, v122, v140
	v_mul_f32_e32 v141, v91, v153
	v_mul_f32_e32 v141, v123, v141
	global_store_dwordx4 v161, v[138:141], s[10:11] offset:2048
	v_mul_f32_e32 v142, v92, v153
	v_mul_f32_e32 v142, v124, v142
	v_mul_f32_e32 v143, v93, v153
	v_mul_f32_e32 v143, v125, v143
	v_mul_f32_e32 v144, v94, v153
	v_mul_f32_e32 v144, v126, v144
	v_mul_f32_e32 v145, v95, v153
	v_mul_f32_e32 v145, v127, v145
	global_store_dwordx4 v161, v[142:145], s[10:11] offset:3072
	s_mul_i32 s13, s68, 3
	s_add_u32 s13, s13, s12
	s_mul_i32 s16, s2, 3
	s_cmp_le_u32 s13, 0x7fff
	s_cselect_b32 s16, s16, 0
	s_add_u32 s14, s10, s16
	s_addc_u32 s15, s11, 0
	global_load_dwordx4 v[80:83], v161, s[14:15]
	global_load_dwordx4 v[84:87], v161, s[14:15] offset:1024
	global_load_dwordx4 v[88:91], v161, s[14:15] offset:2048
	global_load_dwordx4 v[92:95], v161, s[14:15] offset:3072
	s_add_u32 s12, s12, s68
	s_add_u32 s10, s10, s2
	s_addc_u32 s11, s11, s3
	s_cmp_gt_u32 s12, 0x7fff
	s_cbranch_scc1 .Lnf_fin_exit
	s_waitcnt vmcnt(16)
	v_mul_f32_e32 v146, v97, v97
	v_mul_f32_e32 v147, v99, v99
	v_fmac_f32_e32 v146, v96, v96
	v_fmac_f32_e32 v147, v98, v98
	v_add_f32_e32 v148, v146, v147
	v_mul_f32_e32 v146, v101, v101
	v_mul_f32_e32 v147, v103, v103
	v_fmac_f32_e32 v146, v100, v100
	v_fmac_f32_e32 v147, v102, v102
	v_add_f32_e32 v146, v146, v147
	v_add_f32_e32 v148, v148, v146
	v_mul_f32_e32 v146, v105, v105
	v_mul_f32_e32 v147, v107, v107
	v_fmac_f32_e32 v146, v104, v104
	v_fmac_f32_e32 v147, v106, v106
	v_add_f32_e32 v146, v146, v147
	v_add_f32_e32 v148, v148, v146
	v_mul_f32_e32 v146, v109, v109
	v_mul_f32_e32 v147, v111, v111
	v_fmac_f32_e32 v146, v108, v108
	v_fmac_f32_e32 v147, v110, v110
	v_add_f32_e32 v146, v146, v147
	v_add_f32_e32 v148, v148, v146
	ds_bpermute_b32 v146, v162, v148
	s_waitcnt lgkmcnt(0)
	v_add_f32_e32 v148, v148, v146
	ds_bpermute_b32 v146, v163, v148
	s_waitcnt lgkmcnt(0)
	v_add_f32_e32 v148, v148, v146
	ds_bpermute_b32 v146, v164, v148
	s_waitcnt lgkmcnt(0)
	v_add_f32_e32 v148, v148, v146
	ds_bpermute_b32 v146, v165, v148
	s_waitcnt lgkmcnt(0)
	v_add_f32_e32 v148, v148, v146
	ds_bpermute_b32 v146, v166, v148
	s_waitcnt lgkmcnt(0)
	v_add_f32_e32 v148, v148, v146
	ds_bpermute_b32 v146, v167, v148
	s_waitcnt lgkmcnt(0)
; __device__ __forceinline__ void phase_final(const Params& P) {
;     ...
;     for (int r = gw; r < NBATCH * SEQ; r += NGW) {
;         float* xr = P.out + (size_t)r * DM;
;         f32x4 v[4]; float s2 = 0.f;
; #pragma unroll
;         for (int j = 0; j < 4; ++j) { v[j] = *((const f32x4*)xr + lane + 64 * j); s2 += (v[j].x * v[j].x + v[j].y * v[j].y) + (v[j].z * v[j].z + v[j].w * v[j].w); }
;         const float rstd = 1.0f / sqrtf(wave_sum(s2, lane) * (1.0f / DM) + RMS_EPS);
; #pragma unroll
;         for (int j = 0; j < 4; ++j) { const f32x4 g = *((const f32x4*)P.final_norm + lane + 64 * j); *((f32x4*)xr + lane + 64 * j) = v[j] * rstd * g; }
;     }
	v_add_f32_e32 v148, v148, v146
	v_fmamk_f32 v148, v148, 0x3a800000, v154
	v_mul_f32_e32 v146, 0x4f800000, v148
	v_cmp_gt_f32_e32 vcc, 0xf800000, v148
	s_nop 1
	v_cndmask_b32_e32 v148, v148, v146, vcc
	v_sqrt_f32_e32 v146, v148
	s_nop 0
	v_add_u32_e32 v149, -1, v146
	v_add_u32_e32 v150, 1, v146
	v_fma_f32 v151, -v149, v146, v148
	v_fma_f32 v152, -v150, v146, v148
	v_cmp_ge_f32_e64 s[18:19], 0, v151
	s_nop 1
	v_cndmask_b32_e64 v146, v146, v149, s[18:19]
	v_cmp_lt_f32_e64 s[18:19], 0, v152
	s_nop 1
	v_cndmask_b32_e64 v146, v146, v150, s[18:19]
	v_mul_f32_e32 v149, 0x37800000, v146
	v_cndmask_b32_e32 v146, v146, v149, vcc
	v_cmp_class_f32_e32 vcc, v148, v155
	s_nop 1
	v_cndmask_b32_e32 v148, v146, v148, vcc
	v_div_scale_f32 v146, s[18:19], v148, v148, 1.0
	v_rcp_f32_e32 v149, v146
	v_div_scale_f32 v150, vcc, 1.0, v148, 1.0
	v_fma_f32 v151, -v146, v149, 1.0
	v_fmac_f32_e32 v149, v151, v149
	v_mul_f32_e32 v151, v150, v149
	v_fma_f32 v152, -v146, v151, v150
	v_fmac_f32_e32 v151, v152, v149
	v_fma_f32 v146, -v146, v151, v150
	v_div_fmas_f32 v146, v146, v149, v151
	v_div_fixup_f32 v153, v146, v148, 1.0
	v_mul_f32_e32 v130, v96, v153
	v_mul_f32_e32 v130, v112, v130
	v_mul_f32_e32 v131, v97, v153
	v_mul_f32_e32 v131, v113, v131
	v_mul_f32_e32 v132, v98, v153
	v_mul_f32_e32 v132, v114, v132
	v_mul_f32_e32 v133, v99, v153
	v_mul_f32_e32 v133, v115, v133
	global_store_dwordx4 v161, v[130:133], s[10:11]
	v_mul_f32_e32 v134, v100, v153
	v_mul_f32_e32 v134, v116, v134
	v_mul_f32_e32 v135, v101, v153
	v_mul_f32_e32 v135, v117, v135
	v_mul_f32_e32 v136, v102, v153
	v_mul_f32_e32 v136, v118, v136
	v_mul_f32_e32 v137, v103, v153
	v_mul_f32_e32 v137, v119, v137
	global_store_dwordx4 v161, v[134:137], s[10:11] offset:1024
	v_mul_f32_e32 v138, v104, v153
	v_mul_f32_e32 v138, v120, v138
	v_mul_f32_e32 v139, v105, v153
	v_mul_f32_e32 v139, v121, v139
	v_mul_f32_e32 v140, v106, v153
	v_mul_f32_e32 v140, v122, v140
	v_mul_f32_e32 v141, v107, v153
	v_mul_f32_e32 v141, v123, v141
	global_store_dwordx4 v161, v[138:141], s[10:11] offset:2048
	v_mul_f32_e32 v142, v108, v153
	v_mul_f32_e32 v142, v124, v142
	v_mul_f32_e32 v143, v109, v153
	v_mul_f32_e32 v143, v125, v143
	v_mul_f32_e32 v144, v110, v153
	v_mul_f32_e32 v144, v126, v144
	v_mul_f32_e32 v145, v111, v153
	v_mul_f32_e32 v145, v127, v145
	global_store_dwordx4 v161, v[142:145], s[10:11] offset:3072
	s_mul_i32 s13, s68, 3
	s_add_u32 s13, s13, s12
	s_mul_i32 s16, s2, 3
	s_cmp_le_u32 s13, 0x7fff
	s_cselect_b32 s16, s16, 0
	s_add_u32 s14, s10, s16
	s_addc_u32 s15, s11, 0
	global_load_dwordx4 v[96:99], v161, s[14:15]
	global_load_dwordx4 v[100:103], v161, s[14:15] offset:1024
	global_load_dwordx4 v[104:107], v161, s[14:15] offset:2048
	global_load_dwordx4 v[108:111], v161, s[14:15] offset:3072
	s_add_u32 s12, s12, s68
	s_add_u32 s10, s10, s2
	s_addc_u32 s11, s11, s3
	s_cmp_gt_u32 s12, 0x7fff
	s_cbranch_scc1 .Lnf_fin_exit
.Lnf_fin_loop:
	s_waitcnt vmcnt(16)
	v_mul_f32_e32 v146, v65, v65
	v_mul_f32_e32 v147, v67, v67
	v_fmac_f32_e32 v146, v64, v64
	v_fmac_f32_e32 v147, v66, v66
	v_add_f32_e32 v148, v146, v147
	v_mul_f32_e32 v146, v69, v69
	v_mul_f32_e32 v147, v71, v71
	v_fmac_f32_e32 v146, v68, v68
	v_fmac_f32_e32 v147, v70, v70
	v_add_f32_e32 v146, v146, v147
	v_add_f32_e32 v148, v148, v146
	v_mul_f32_e32 v146, v73, v73
	v_mul_f32_e32 v147, v75, v75
	v_fmac_f32_e32 v146, v72, v72
	v_fmac_f32_e32 v147, v74, v74
	v_add_f32_e32 v146, v146, v147
	v_add_f32_e32 v148, v148, v146
	v_mul_f32_e32 v146, v77, v77
	v_mul_f32_e32 v147, v79, v79
	v_fmac_f32_e32 v146, v76, v76
	v_fmac_f32_e32 v147, v78, v78
	v_add_f32_e32 v146, v146, v147
	v_add_f32_e32 v148, v148, v146
	ds_bpermute_b32 v146, v162, v148
	s_waitcnt lgkmcnt(0)
	v_add_f32_e32 v148, v148, v146
	ds_bpermute_b32 v146, v163, v148
	s_waitcnt lgkmcnt(0)
	v_add_f32_e32 v148, v148, v146
	ds_bpermute_b32 v146, v164, v148
	s_waitcnt lgkmcnt(0)
	v_add_f32_e32 v148, v148, v146
	ds_bpermute_b32 v146, v165, v148
	s_waitcnt lgkmcnt(0)
	v_add_f32_e32 v148, v148, v146
	ds_bpermute_b32 v146, v166, v148
	s_waitcnt lgkmcnt(0)
	v_add_f32_e32 v148, v148, v146
	ds_bpermute_b32 v146, v167, v148
	s_waitcnt lgkmcnt(0)
	v_add_f32_e32 v148, v148, v146
	v_fmamk_f32 v148, v148, 0x3a800000, v154
	v_mul_f32_e32 v146, 0x4f800000, v148
	v_cmp_gt_f32_e32 vcc, 0xf800000, v148
	s_nop 1
	v_cndmask_b32_e32 v148, v148, v146, vcc
	v_sqrt_f32_e32 v146, v148
	s_nop 0
	v_add_u32_e32 v149, -1, v146
	v_add_u32_e32 v150, 1, v146
	v_fma_f32 v151, -v149, v146, v148
	v_fma_f32 v152, -v150, v146, v148
	v_cmp_ge_f32_e64 s[18:19], 0, v151
	s_nop 1
	v_cndmask_b32_e64 v146, v146, v149, s[18:19]
	v_cmp_lt_f32_e64 s[18:19], 0, v152
	s_nop 1
	v_cndmask_b32_e64 v146, v146, v150, s[18:19]
	v_mul_f32_e32 v149, 0x37800000, v146
	v_cndmask_b32_e32 v146, v146, v149, vcc
	v_cmp_class_f32_e32 vcc, v148, v155
	s_nop 1
	v_cndmask_b32_e32 v148, v146, v148, vcc
	v_div_scale_f32 v146, s[18:19], v148, v148, 1.0
	v_rcp_f32_e32 v149, v146
	v_div_scale_f32 v150, vcc, 1.0, v148, 1.0
	v_fma_f32 v151, -v146, v149, 1.0
	v_fmac_f32_e32 v149, v151, v149
	v_mul_f32_e32 v151, v150, v149
	v_fma_f32 v152, -v146, v151, v150
	v_fmac_f32_e32 v151, v152, v149
	v_fma_f32 v146, -v146, v151, v150
	v_div_fmas_f32 v146, v146, v149, v151
	v_div_fixup_f32 v153, v146, v148, 1.0
	v_mul_f32_e32 v130, v64, v153
	v_mul_f32_e32 v130, v112, v130
	v_mul_f32_e32 v131, v65, v153
	v_mul_f32_e32 v131, v113, v131
	v_mul_f32_e32 v132, v66, v153
	v_mul_f32_e32 v132, v114, v132
	v_mul_f32_e32 v133, v67, v153
	v_mul_f32_e32 v133, v115, v133
	global_store_dwordx4 v161, v[130:133], s[10:11]
	v_mul_f32_e32 v134, v68, v153
	v_mul_f32_e32 v134, v116, v134
	v_mul_f32_e32 v135, v69, v153
	v_mul_f32_e32 v135, v117, v135
	v_mul_f32_e32 v136, v70, v153
	v_mul_f32_e32 v136, v118, v136
	v_mul_f32_e32 v137, v71, v153
	v_mul_f32_e32 v137, v119, v137
	global_store_dwordx4 v161, v[134:137], s[10:11] offset:1024
	v_mul_f32_e32 v138, v72, v153
	v_mul_f32_e32 v138, v120, v138
	v_mul_f32_e32 v139, v73, v153
	v_mul_f32_e32 v139, v121, v139
	v_mul_f32_e32 v140, v74, v153
	v_mul_f32_e32 v140, v122, v140
	v_mul_f32_e32 v141, v75, v153
	v_mul_f32_e32 v141, v123, v141
	global_store_dwordx4 v161, v[138:141], s[10:11] offset:2048
	v_mul_f32_e32 v142, v76, v153
	v_mul_f32_e32 v142, v124, v142
	v_mul_f32_e32 v143, v77, v153
	v_mul_f32_e32 v143, v125, v143
	v_mul_f32_e32 v144, v78, v153
	v_mul_f32_e32 v144, v126, v144
	v_mul_f32_e32 v145, v79, v153
	v_mul_f32_e32 v145, v127, v145
	global_store_dwordx4 v161, v[142:145], s[10:11] offset:3072
	s_mul_i32 s13, s68, 3
	s_add_u32 s13, s13, s12
	s_mul_i32 s16, s2, 3
	s_cmp_le_u32 s13, 0x7fff
	s_cselect_b32 s16, s16, 0
	s_add_u32 s14, s10, s16
	s_addc_u32 s15, s11, 0
	global_load_dwordx4 v[64:67], v161, s[14:15]
	global_load_dwordx4 v[68:71], v161, s[14:15] offset:1024
	global_load_dwordx4 v[72:75], v161, s[14:15] offset:2048
	global_load_dwordx4 v[76:79], v161, s[14:15] offset:3072
	s_add_u32 s12, s12, s68
	s_add_u32 s10, s10, s2
	s_addc_u32 s11, s11, s3
	s_cmp_gt_u32 s12, 0x7fff
	s_cbranch_scc1 .Lnf_fin_exit
; __device__ __forceinline__ void phase_final(const Params& P) {
;     ...
;     for (int r = gw; r < NBATCH * SEQ; r += NGW) {
;         float* xr = P.out + (size_t)r * DM;
;         f32x4 v[4]; float s2 = 0.f;
; #pragma unroll
;         for (int j = 0; j < 4; ++j) { v[j] = *((const f32x4*)xr + lane + 64 * j); s2 += (v[j].x * v[j].x + v[j].y * v[j].y) + (v[j].z * v[j].z + v[j].w * v[j].w); }
;         const float rstd = 1.0f / sqrtf(wave_sum(s2, lane) * (1.0f / DM) + RMS_EPS);
; #pragma unroll
;         for (int j = 0; j < 4; ++j) { const f32x4 g = *((const f32x4*)P.final_norm + lane + 64 * j); *((f32x4*)xr + lane + 64 * j) = v[j] * rstd * g; }
;     }
	s_waitcnt vmcnt(16)
	v_mul_f32_e32 v146, v81, v81
	v_mul_f32_e32 v147, v83, v83
	v_fmac_f32_e32 v146, v80, v80
	v_fmac_f32_e32 v147, v82, v82
	v_add_f32_e32 v148, v146, v147
	v_mul_f32_e32 v146, v85, v85
	v_mul_f32_e32 v147, v87, v87
	v_fmac_f32_e32 v146, v84, v84
	v_fmac_f32_e32 v147, v86, v86
	v_add_f32_e32 v146, v146, v147
	v_add_f32_e32 v148, v148, v146
	v_mul_f32_e32 v146, v89, v89
	v_mul_f32_e32 v147, v91, v91
	v_fmac_f32_e32 v146, v88, v88
	v_fmac_f32_e32 v147, v90, v90
	v_add_f32_e32 v146, v146, v147
	v_add_f32_e32 v148, v148, v146
	v_mul_f32_e32 v146, v93, v93
	v_mul_f32_e32 v147, v95, v95
	v_fmac_f32_e32 v146, v92, v92
	v_fmac_f32_e32 v147, v94, v94
	v_add_f32_e32 v146, v146, v147
	v_add_f32_e32 v148, v148, v146
	ds_bpermute_b32 v146, v162, v148
	s_waitcnt lgkmcnt(0)
	v_add_f32_e32 v148, v148, v146
	ds_bpermute_b32 v146, v163, v148
	s_waitcnt lgkmcnt(0)
	v_add_f32_e32 v148, v148, v146
	ds_bpermute_b32 v146, v164, v148
	s_waitcnt lgkmcnt(0)
	v_add_f32_e32 v148, v148, v146
	ds_bpermute_b32 v146, v165, v148
	s_waitcnt lgkmcnt(0)
	v_add_f32_e32 v148, v148, v146
	ds_bpermute_b32 v146, v166, v148
	s_waitcnt lgkmcnt(0)
	v_add_f32_e32 v148, v148, v146
	ds_bpermute_b32 v146, v167, v148
	s_waitcnt lgkmcnt(0)
	v_add_f32_e32 v148, v148, v146
	v_fmamk_f32 v148, v148, 0x3a800000, v154
	v_mul_f32_e32 v146, 0x4f800000, v148
	v_cmp_gt_f32_e32 vcc, 0xf800000, v148
	s_nop 1
	v_cndmask_b32_e32 v148, v148, v146, vcc
	v_sqrt_f32_e32 v146, v148
	s_nop 0
	v_add_u32_e32 v149, -1, v146
	v_add_u32_e32 v150, 1, v146
	v_fma_f32 v151, -v149, v146, v148
	v_fma_f32 v152, -v150, v146, v148
	v_cmp_ge_f32_e64 s[18:19], 0, v151
	s_nop 1
	v_cndmask_b32_e64 v146, v146, v149, s[18:19]
	v_cmp_lt_f32_e64 s[18:19], 0, v152
	s_nop 1
	v_cndmask_b32_e64 v146, v146, v150, s[18:19]
	v_mul_f32_e32 v149, 0x37800000, v146
	v_cndmask_b32_e32 v146, v146, v149, vcc
	v_cmp_class_f32_e32 vcc, v148, v155
	s_nop 1
	v_cndmask_b32_e32 v148, v146, v148, vcc
	v_div_scale_f32 v146, s[18:19], v148, v148, 1.0
	v_rcp_f32_e32 v149, v146
	v_div_scale_f32 v150, vcc, 1.0, v148, 1.0
	v_fma_f32 v151, -v146, v149, 1.0
	v_fmac_f32_e32 v149, v151, v149
	v_mul_f32_e32 v151, v150, v149
	v_fma_f32 v152, -v146, v151, v150
	v_fmac_f32_e32 v151, v152, v149
	v_fma_f32 v146, -v146, v151, v150
	v_div_fmas_f32 v146, v146, v149, v151
	v_div_fixup_f32 v153, v146, v148, 1.0
	v_mul_f32_e32 v130, v80, v153
	v_mul_f32_e32 v130, v112, v130
	v_mul_f32_e32 v131, v81, v153
	v_mul_f32_e32 v131, v113, v131
	v_mul_f32_e32 v132, v82, v153
	v_mul_f32_e32 v132, v114, v132
	v_mul_f32_e32 v133, v83, v153
	v_mul_f32_e32 v133, v115, v133
	global_store_dwordx4 v161, v[130:133], s[10:11]
	v_mul_f32_e32 v134, v84, v153
	v_mul_f32_e32 v134, v116, v134
	v_mul_f32_e32 v135, v85, v153
	v_mul_f32_e32 v135, v117, v135
	v_mul_f32_e32 v136, v86, v153
	v_mul_f32_e32 v136, v118, v136
	v_mul_f32_e32 v137, v87, v153
	v_mul_f32_e32 v137, v119, v137
	global_store_dwordx4 v161, v[134:137], s[10:11] offset:1024
	v_mul_f32_e32 v138, v88, v153
	v_mul_f32_e32 v138, v120, v138
	v_mul_f32_e32 v139, v89, v153
	v_mul_f32_e32 v139, v121, v139
	v_mul_f32_e32 v140, v90, v153
	v_mul_f32_e32 v140, v122, v140
	v_mul_f32_e32 v141, v91, v153
	v_mul_f32_e32 v141, v123, v141
	global_store_dwordx4 v161, v[138:141], s[10:11] offset:2048
	v_mul_f32_e32 v142, v92, v153
	v_mul_f32_e32 v142, v124, v142
	v_mul_f32_e32 v143, v93, v153
	v_mul_f32_e32 v143, v125, v143
	v_mul_f32_e32 v144, v94, v153
	v_mul_f32_e32 v144, v126, v144
	v_mul_f32_e32 v145, v95, v153
	v_mul_f32_e32 v145, v127, v145
	global_store_dwordx4 v161, v[142:145], s[10:11] offset:3072
	s_mul_i32 s13, s68, 3
	s_add_u32 s13, s13, s12
	s_mul_i32 s16, s2, 3
	s_cmp_le_u32 s13, 0x7fff
	s_cselect_b32 s16, s16, 0
	s_add_u32 s14, s10, s16
	s_addc_u32 s15, s11, 0
	global_load_dwordx4 v[80:83], v161, s[14:15]
	global_load_dwordx4 v[84:87], v161, s[14:15] offset:1024
	global_load_dwordx4 v[88:91], v161, s[14:15] offset:2048
	global_load_dwordx4 v[92:95], v161, s[14:15] offset:3072
	s_add_u32 s12, s12, s68
	s_add_u32 s10, s10, s2
	s_addc_u32 s11, s11, s3
	s_cmp_gt_u32 s12, 0x7fff
	s_cbranch_scc1 .Lnf_fin_exit
; __device__ __forceinline__ void phase_final(const Params& P) {
;     ...
;     for (int r = gw; r < NBATCH * SEQ; r += NGW) {
;         float* xr = P.out + (size_t)r * DM;
;         f32x4 v[4]; float s2 = 0.f;
; #pragma unroll
;         for (int j = 0; j < 4; ++j) { v[j] = *((const f32x4*)xr + lane + 64 * j); s2 += (v[j].x * v[j].x + v[j].y * v[j].y) + (v[j].z * v[j].z + v[j].w * v[j].w); }
;         const float rstd = 1.0f / sqrtf(wave_sum(s2, lane) * (1.0f / DM) + RMS_EPS);
; #pragma unroll
;         for (int j = 0; j < 4; ++j) { const f32x4 g = *((const f32x4*)P.final_norm + lane + 64 * j); *((f32x4*)xr + lane + 64 * j) = v[j] * rstd * g; }
;     }
; }
	s_waitcnt vmcnt(16)
	v_mul_f32_e32 v146, v97, v97
	v_mul_f32_e32 v147, v99, v99
	v_fmac_f32_e32 v146, v96, v96
	v_fmac_f32_e32 v147, v98, v98
	v_add_f32_e32 v148, v146, v147
	v_mul_f32_e32 v146, v101, v101
	v_mul_f32_e32 v147, v103, v103
	v_fmac_f32_e32 v146, v100, v100
	v_fmac_f32_e32 v147, v102, v102
	v_add_f32_e32 v146, v146, v147
	v_add_f32_e32 v148, v148, v146
	v_mul_f32_e32 v146, v105, v105
	v_mul_f32_e32 v147, v107, v107
	v_fmac_f32_e32 v146, v104, v104
	v_fmac_f32_e32 v147, v106, v106
	v_add_f32_e32 v146, v146, v147
	v_add_f32_e32 v148, v148, v146
	v_mul_f32_e32 v146, v109, v109
	v_mul_f32_e32 v147, v111, v111
	v_fmac_f32_e32 v146, v108, v108
	v_fmac_f32_e32 v147, v110, v110
	v_add_f32_e32 v146, v146, v147
	v_add_f32_e32 v148, v148, v146
	ds_bpermute_b32 v146, v162, v148
	s_waitcnt lgkmcnt(0)
	v_add_f32_e32 v148, v148, v146
	ds_bpermute_b32 v146, v163, v148
	s_waitcnt lgkmcnt(0)
	v_add_f32_e32 v148, v148, v146
	ds_bpermute_b32 v146, v164, v148
	s_waitcnt lgkmcnt(0)
	v_add_f32_e32 v148, v148, v146
	ds_bpermute_b32 v146, v165, v148
	s_waitcnt lgkmcnt(0)
	v_add_f32_e32 v148, v148, v146
	ds_bpermute_b32 v146, v166, v148
	s_waitcnt lgkmcnt(0)
	v_add_f32_e32 v148, v148, v146
	ds_bpermute_b32 v146, v167, v148
	s_waitcnt lgkmcnt(0)
	v_add_f32_e32 v148, v148, v146
	v_fmamk_f32 v148, v148, 0x3a800000, v154
	v_mul_f32_e32 v146, 0x4f800000, v148
	v_cmp_gt_f32_e32 vcc, 0xf800000, v148
	s_nop 1
	v_cndmask_b32_e32 v148, v148, v146, vcc
	v_sqrt_f32_e32 v146, v148
	s_nop 0
	v_add_u32_e32 v149, -1, v146
	v_add_u32_e32 v150, 1, v146
	v_fma_f32 v151, -v149, v146, v148
	v_fma_f32 v152, -v150, v146, v148
	v_cmp_ge_f32_e64 s[18:19], 0, v151
	s_nop 1
	v_cndmask_b32_e64 v146, v146, v149, s[18:19]
	v_cmp_lt_f32_e64 s[18:19], 0, v152
	s_nop 1
	v_cndmask_b32_e64 v146, v146, v150, s[18:19]
	v_mul_f32_e32 v149, 0x37800000, v146
	v_cndmask_b32_e32 v146, v146, v149, vcc
	v_cmp_class_f32_e32 vcc, v148, v155
	s_nop 1
	v_cndmask_b32_e32 v148, v146, v148, vcc
	v_div_scale_f32 v146, s[18:19], v148, v148, 1.0
	v_rcp_f32_e32 v149, v146
	v_div_scale_f32 v150, vcc, 1.0, v148, 1.0
	v_fma_f32 v151, -v146, v149, 1.0
	v_fmac_f32_e32 v149, v151, v149
	v_mul_f32_e32 v151, v150, v149
	v_fma_f32 v152, -v146, v151, v150
	v_fmac_f32_e32 v151, v152, v149
	v_fma_f32 v146, -v146, v151, v150
	v_div_fmas_f32 v146, v146, v149, v151
	v_div_fixup_f32 v153, v146, v148, 1.0
	v_mul_f32_e32 v130, v96, v153
	v_mul_f32_e32 v130, v112, v130
	v_mul_f32_e32 v131, v97, v153
	v_mul_f32_e32 v131, v113, v131
	v_mul_f32_e32 v132, v98, v153
	v_mul_f32_e32 v132, v114, v132
	v_mul_f32_e32 v133, v99, v153
	v_mul_f32_e32 v133, v115, v133
	global_store_dwordx4 v161, v[130:133], s[10:11]
	v_mul_f32_e32 v134, v100, v153
	v_mul_f32_e32 v134, v116, v134
	v_mul_f32_e32 v135, v101, v153
	v_mul_f32_e32 v135, v117, v135
	v_mul_f32_e32 v136, v102, v153
	v_mul_f32_e32 v136, v118, v136
	v_mul_f32_e32 v137, v103, v153
	v_mul_f32_e32 v137, v119, v137
	global_store_dwordx4 v161, v[134:137], s[10:11] offset:1024
	v_mul_f32_e32 v138, v104, v153
	v_mul_f32_e32 v138, v120, v138
	v_mul_f32_e32 v139, v105, v153
	v_mul_f32_e32 v139, v121, v139
	v_mul_f32_e32 v140, v106, v153
	v_mul_f32_e32 v140, v122, v140
	v_mul_f32_e32 v141, v107, v153
	v_mul_f32_e32 v141, v123, v141
	global_store_dwordx4 v161, v[138:141], s[10:11] offset:2048
	v_mul_f32_e32 v142, v108, v153
	v_mul_f32_e32 v142, v124, v142
	v_mul_f32_e32 v143, v109, v153
	v_mul_f32_e32 v143, v125, v143
	v_mul_f32_e32 v144, v110, v153
	v_mul_f32_e32 v144, v126, v144
	v_mul_f32_e32 v145, v111, v153
	v_mul_f32_e32 v145, v127, v145
	global_store_dwordx4 v161, v[142:145], s[10:11] offset:3072
	s_mul_i32 s13, s68, 3
	s_add_u32 s13, s13, s12
	s_mul_i32 s16, s2, 3
	s_cmp_le_u32 s13, 0x7fff
	s_cselect_b32 s16, s16, 0
	s_add_u32 s14, s10, s16
	s_addc_u32 s15, s11, 0
	global_load_dwordx4 v[96:99], v161, s[14:15]
	global_load_dwordx4 v[100:103], v161, s[14:15] offset:1024
	global_load_dwordx4 v[104:107], v161, s[14:15] offset:2048
	global_load_dwordx4 v[108:111], v161, s[14:15] offset:3072
	s_add_u32 s12, s12, s68
	s_add_u32 s10, s10, s2
	s_addc_u32 s11, s11, s3
	s_cmp_gt_u32 s12, 0x7fff
	s_cbranch_scc1 .Lnf_fin_exit
	s_branch .Lnf_fin_loop
.Lnf_fin_exit:
	s_waitcnt vmcnt(0)
.LBB0_1218:
	s_endpgm
